# issue small_gemm<1,1,4,2> prologue stages inside the last K iteration of the big GEMM (in the LDS slots the dummy next-unit prefetch used), last two pieces at epilogue entry; out-proj, Q, Wo, MLP-down
# baseline (speedup 1.0000x reference)
;     DI bool next(int i, Unit& u) const { const int L = i * 32 + rank; if (L >= ppg * nN) return false; u.pm = ppg * grp + (L % ppg); const int p0 = L / ppg, p1 = p0 + rot; u.pn = rev ? nN - 1 - p0 : (p1 >= nN ? p1 - nN : p1); return true; }
; #define PG8_LDA(dst, b, h) do { _Pragma("unroll") for (int m = 0; m < 4; ++m) _Pragma("unroll") for (int k = 0; k < 2; ++k) dst[m][k] = *(const PG8_LAS bf16x8*)(lds + PG8_SA(b, h) + aoff + m * 2048 + k * 1024); } while (0)
; template <class Epi, class Sched, bool ALIGN_EPI = false, bool SP2 = false>
; __device__ __forceinline__ void gemm_phase(PG8_LAS unsigned char* lds, const Gemm g, const Sched& S, const Epi& E, const int tid) {
;     ...
;         const bool has_next = S.next(ui + 1, nxt);
;         const char* nA = has_next ? (const char*)g.A + (size_t)nxt.pm * tstep : cA; const char* nB = has_next ? (const char*)g.Bt + (size_t)nxt.pn * tstep : cB;
;         for (int t = 0; t < nt; t += 2) {
;             const bool last = (t == nt - 2);
;             const char* a1 = cA + (size_t)(t + 1) * kstep;
;             const char* a2 = last ? nA : cA + (size_t)(t + 2) * kstep; const char* b2 = last ? nB : cB + (size_t)(t + 2) * kstep;
;             const char* a3 = a2 + kstep; const char* b3 = b2 + kstep;
;             if (last && has_next) S.a_ready(nxt);
;             if constexpr (SP2) {
;             PG8_LDB(B0, 0, 0); PG8_LDB(B1, 0, 1); PG8_SCHED; PG8_LDA(At, 0, 0); PG8_STAGE(PG8_SA(1, 1), a1 + hstep, voffA);
;             PG8_WAIT_V(8); PG8_WAIT_L(0); PG8_BAR; PG8_MMA(0, 0, At, B0); PG8_MMA(0, 1, At, B1); PG8_BAR; PG8_SCHED;
;             PG8_LDA(At, 0, 1); PG8_STAGE(PG8_SB(0, 0), b2, voffB); PG8_STAGE(PG8_SB(0, 1), b2 + hstepB, voffB); PG8_STAGE(PG8_SA(0, 0), a2, voffA);
;             PG8_WAIT_V(8); PG8_WAIT_L(0); PG8_BAR; PG8_MMA(1, 0, At, B0); PG8_MMA(1, 1, At, B1); PG8_BAR; PG8_SCHED;
; template <int RA, int NP, int NS, int KT, class R8>
; DI void small_gemm(LAS unsigned char* lds, const bf16* __restrict__ A, const bf16* __restrict__ Bt, int K, int row_base, int col_base, const R8& e, int tid, int wave, int lane) {
;     ...
;     int R, Cc; pg8::stage_rc(tid * 16, R, Cc);
;     const int Rb = (R & ~31) + pg8::perm32(R & 31);
;     const bf16* asrc = A + (size_t)(row_base + R) * K + Cc;
;     const bf16* bsrc = Bt + (size_t)(col_base + Rb) * K + Cc;
;     const size_t bgrp = (size_t)64 * K;
;     const int NT = K / (64 * KT);
.LBB0_979:
	s_add_u32 s36, s38, 0xfffc0080
	s_addc_u32 s37, s39, -1
	s_add_i32 s81, 0, 0x10000
	s_cmp_eq_u32 s80, 12
	s_cselect_b32 s41, s19, s37
	s_cselect_b32 s40, s25, s36
	v_add_u32_e32 v150, s81, v158
	s_cselect_b32 s37, s17, s79
	s_cselect_b32 s36, s76, s78
	s_cmp_eq_u32 s80, 12
	s_cselect_b32 s32, 1, 0
	s_andn2_b32 s32, s32, s30
	s_cmp_lg_u32 s32, 0
	s_cbranch_scc0 .Leh2_t
	s_lshl_b32 s92, s3, 2
	s_andn2_b32 s92, s92, 63
	s_lshl_b32 s93, s34, 6
	v_and_b32_e32 v212, 0xffffffe0, v133
	v_or_b32_e32 v214, s92, v154
	s_lshl_b32 s98, s27, 7
	s_and_b32 s93, s93, 64
	v_and_b32_e32 v213, 24, v155
	v_add_u32_e32 v212, v214, v212
	s_or_b32 s98, s93, s98
	s_lshr_b32 s93, s42, 31
	v_or3_b32 v212, v212, v213, v153
	s_bitset1_b32 s98, 14
	s_add_i32 s93, s42, s93
	v_ashrrev_i32_e32 v213, 31, v212
	s_ashr_i32 s99, s93, 1
	v_add_u32_e32 v216, s98, v133
	v_lshlrev_b64 v[212:213], 11, v[212:213]
	v_ashrrev_i32_e32 v217, 31, v216
	v_lshl_add_u64 v[212:213], s[10:11], 0, v[212:213]
	s_lshl_b32 s41, s99, 4
	v_mov_b32_e32 v234, v132
	v_ashrrev_i32_e32 v235, 31, v132
	s_add_i32 s98, s98, s41
	v_lshlrev_b64 v[216:217], 11, v[216:217]
	v_lshlrev_b64 v[218:219], 1, v[234:235]
	v_or_b32_e32 v224, s98, v152
	v_lshl_add_u64 v[216:217], s[6:7], 0, v[216:217]
	s_add_i32 s98, s43, 0
	v_lshl_add_u64 v[230:231], v[216:217], 0, v[218:219]
	v_lshl_add_u64 v[228:229], v[212:213], 0, v[218:219]
	s_mov_b32 s100, 0x200
	s_mov_b32 s101, 0
	v_lshl_add_u64 v[252:253], v[230:231], 0, s[100:101]
	v_lshl_add_u64 v[254:255], v[228:229], 0, s[100:101]
	s_mov_b32 s100, 0xfffffd80
	s_mov_b32 s101, -1
.Leh2_t:
	s_add_i32 s84, 0, 0x14000
	ds_read_b128 v[146:149], v150
	ds_read_b128 v[162:165], v150 offset:1024
	ds_read_b128 v[170:173], v150 offset:2048
	ds_read_b128 v[174:177], v150 offset:3072
	v_add_u32_e32 v150, s84, v158
	ds_read_b128 v[178:181], v150
	ds_read_b128 v[182:185], v150 offset:1024
	ds_read_b128 v[186:189], v150 offset:2048
	ds_read_b128 v[190:193], v150 offset:3072
	v_lshl_add_u64 v[150:151], s[38:39], 0, v[142:143]
	s_add_i32 m0, s29, 0xc000
	ds_read_b128 v[194:197], v160
	ds_read_b128 v[198:201], v160 offset:1024
	ds_read_b128 v[212:215], v160 offset:2048
	ds_read_b128 v[216:219], v160 offset:3072
	ds_read_b128 v[220:223], v160 offset:4096
	ds_read_b128 v[224:227], v160 offset:5120
	ds_read_b128 v[228:231], v160 offset:6144
	ds_read_b128 v[232:235], v160 offset:7168
	global_load_lds_dwordx4 v[150:151], off
	v_lshl_add_u64 v[150:151], s[38:39], 0, v[144:145]
	s_add_i32 m0, s29, 0xe000
	s_nop 0
	global_load_lds_dwordx4 v[150:151], off
	s_waitcnt vmcnt(8)
	s_waitcnt lgkmcnt(0)
	s_barrier
	s_setprio 1
	s_waitcnt lgkmcnt(0)
	v_mfma_f32_16x16x32_bf16 v[120:123], v[146:149], v[194:197], v[120:123]
	v_mfma_f32_16x16x32_bf16 v[128:131], v[170:173], v[194:197], v[128:131]
	v_mfma_f32_16x16x32_bf16 v[100:103], v[146:149], v[212:215], v[100:103]
	v_mfma_f32_16x16x32_bf16 v[108:111], v[170:173], v[212:215], v[108:111]
	v_mfma_f32_16x16x32_bf16 v[84:87], v[146:149], v[220:223], v[84:87]
	v_mfma_f32_16x16x32_bf16 v[92:95], v[170:173], v[220:223], v[92:95]
	v_mfma_f32_16x16x32_bf16 v[68:71], v[146:149], v[228:231], v[68:71]
	v_mfma_f32_16x16x32_bf16 v[76:79], v[170:173], v[228:231], v[76:79]
	v_mfma_f32_16x16x32_bf16 v[120:123], v[162:165], v[198:201], v[120:123]
	v_mfma_f32_16x16x32_bf16 v[128:131], v[174:177], v[198:201], v[128:131]
	v_mfma_f32_16x16x32_bf16 v[100:103], v[162:165], v[216:219], v[100:103]
	v_mfma_f32_16x16x32_bf16 v[108:111], v[174:177], v[216:219], v[108:111]
	v_mfma_f32_16x16x32_bf16 v[84:87], v[162:165], v[224:227], v[84:87]
	v_mfma_f32_16x16x32_bf16 v[92:95], v[174:177], v[224:227], v[92:95]
	v_mfma_f32_16x16x32_bf16 v[68:71], v[162:165], v[232:235], v[68:71]
	v_mfma_f32_16x16x32_bf16 v[76:79], v[174:177], v[232:235], v[76:79]
	s_setprio 0
	s_setprio 1
	v_mfma_f32_16x16x32_bf16 v[116:119], v[178:181], v[194:197], v[116:119]
	v_mfma_f32_16x16x32_bf16 v[124:127], v[186:189], v[194:197], v[124:127]
	v_mfma_f32_16x16x32_bf16 v[104:107], v[178:181], v[212:215], v[104:107]
	v_mfma_f32_16x16x32_bf16 v[112:115], v[186:189], v[212:215], v[112:115]
	v_mfma_f32_16x16x32_bf16 v[88:91], v[178:181], v[220:223], v[88:91]
	v_mfma_f32_16x16x32_bf16 v[96:99], v[186:189], v[220:223], v[96:99]
	v_mfma_f32_16x16x32_bf16 v[72:75], v[178:181], v[228:231], v[72:75]
	v_mfma_f32_16x16x32_bf16 v[80:83], v[186:189], v[228:231], v[80:83]
	v_mfma_f32_16x16x32_bf16 v[116:119], v[182:185], v[198:201], v[116:119]
	v_mfma_f32_16x16x32_bf16 v[124:127], v[190:193], v[198:201], v[124:127]
	v_mfma_f32_16x16x32_bf16 v[104:107], v[182:185], v[216:219], v[104:107]
	v_mfma_f32_16x16x32_bf16 v[112:115], v[190:193], v[216:219], v[112:115]
	v_mfma_f32_16x16x32_bf16 v[88:91], v[182:185], v[224:227], v[88:91]
	v_mfma_f32_16x16x32_bf16 v[96:99], v[190:193], v[224:227], v[96:99]
	v_mfma_f32_16x16x32_bf16 v[72:75], v[182:185], v[232:235], v[72:75]
	v_mfma_f32_16x16x32_bf16 v[80:83], v[190:193], v[232:235], v[80:83]
	s_setprio 0
	s_barrier
	s_add_i32 s81, s81, s43
	v_lshl_add_u64 v[150:151], s[36:37], 0, v[136:137]
	s_mov_b32 m0, s81
	ds_read_b128 v[194:197], v160 offset:16384
	ds_read_b128 v[198:201], v160 offset:17408
	ds_read_b128 v[212:215], v160 offset:18432
	ds_read_b128 v[216:219], v160 offset:19456
	ds_read_b128 v[220:223], v160 offset:20480
	ds_read_b128 v[224:227], v160 offset:21504
	ds_read_b128 v[228:231], v160 offset:22528
	ds_read_b128 v[232:235], v160 offset:23552
	s_cmp_lg_u32 s32, 0
	s_cbranch_scc1 .Lbt2_0
	global_load_lds_dwordx4 v[150:151], off
	s_branch .Lbe2_0
; #define PG8_STAGE(bufoff, gbase, voff) do { _Pragma("unroll") for (int _i = 0; _i < 2; ++_i) \
;         __builtin_amdgcn_global_load_lds((const unsigned*)((const char*)(gbase) + (voff)[_i]), (PG8_LAS unsigned*)(lds + (bufoff) + ldsw + _i * 8192), 16, 0, 0); } while (0)
; #define PG8_LDA(dst, b, h) do { _Pragma("unroll") for (int m = 0; m < 4; ++m) _Pragma("unroll") for (int k = 0; k < 2; ++k) dst[m][k] = *(const PG8_LAS bf16x8*)(lds + PG8_SA(b, h) + aoff + m * 2048 + k * 1024); } while (0)
; #define PG8_LDB(dst, b, h) do { _Pragma("unroll") for (int n = 0; n < 2; ++n) _Pragma("unroll") for (int k = 0; k < 2; ++k) dst[n][k] = *(const PG8_LAS bf16x8*)(lds + PG8_SB(b, h) + boff + n * 2048 + k * 1024); } while (0)
; #define PG8_MMA(ai, bj, At, Bt) do { __builtin_amdgcn_s_setprio(1); _Pragma("unroll") for (int m = 0; m < 4; ++m) _Pragma("unroll") for (int n = 0; n < 2; ++n) _Pragma("unroll") for (int k = 0; k < 2; ++k) \
;         acc[ai][bj][m][n] = __builtin_amdgcn_mfma_f32_16x16x32_bf16(Bt[n][k], At[m][k], acc[ai][bj][m][n], 0, 0, 0); __builtin_amdgcn_s_setprio(0); } while (0)
; #define PG8_WAIT_V(n) asm volatile("s_waitcnt vmcnt(" #n ")" ::: "memory")
; #define PG8_WAIT_L(n) asm volatile("s_waitcnt lgkmcnt(" #n ")" ::: "memory")
; #define PG8_BAR __builtin_amdgcn_s_barrier()
; #define PG8_SCHED __builtin_amdgcn_sched_barrier(0)
; template <class Epi, class Sched, bool ALIGN_EPI = false, bool SP2 = false>
; __device__ __forceinline__ void gemm_phase(PG8_LAS unsigned char* lds, const Gemm g, const Sched& S, const Epi& E, const int tid) {
;     ...
;             PG8_LDA(At, 0, 1); PG8_STAGE(PG8_SB(0, 0), b2, voffB); PG8_STAGE(PG8_SB(0, 1), b2 + hstepB, voffB); PG8_STAGE(PG8_SA(0, 0), a2, voffA);
;             PG8_WAIT_V(8); PG8_WAIT_L(0); PG8_BAR; PG8_MMA(1, 0, At, B0); PG8_MMA(1, 1, At, B1); PG8_BAR; PG8_SCHED;
;             PG8_LDB(B0, 1, 0); PG8_LDB(B1, 1, 1); PG8_SCHED; PG8_LDA(At, 1, 0); PG8_STAGE(PG8_SA(0, 1), a2 + hstep, voffA);
.Lbt2_0:
	global_load_lds_dwordx4 v[252:253], off
.Lbe2_0:
	s_add_i32 m0, s81, 0x2000
	s_add_u32 s82, s36, 0x10000
	v_lshl_add_u64 v[166:167], s[36:37], 0, v[140:141]
	s_addc_u32 s83, s37, 0
	s_add_i32 s81, s84, s43
	s_cmp_lg_u32 s32, 0
	s_cbranch_scc1 .Lbt2_1
	global_load_lds_dwordx4 v[166:167], off
	s_branch .Lbe2_1
.Lbt2_1:
	global_load_lds_dwordx4 v[254:255], off
.Lbe2_1:
	v_lshl_add_u64 v[236:237], s[82:83], 0, v[136:137]
	s_mov_b32 m0, s81
	v_lshl_add_u64 v[238:239], s[40:41], 0, v[138:139]
	s_cmp_lg_u32 s32, 0
	s_cbranch_scc1 .Lbt2_2
	global_load_lds_dwordx4 v[236:237], off
	s_branch .Lbe2_2
.Lbt2_2:
	v_lshl_add_u64 v[252:253], v[252:253], 0, s[52:53]
	global_load_lds_dwordx4 v[252:253], off
.Lbe2_2:
	v_lshl_add_u64 v[236:237], s[82:83], 0, v[140:141]
	s_add_i32 m0, s81, 0x2000
	s_nop 0
	s_cmp_lg_u32 s32, 0
	s_cbranch_scc1 .Lbt2_3
	global_load_lds_dwordx4 v[236:237], off
	s_branch .Lbe2_3
.Lbt2_3:
	v_lshl_add_u64 v[254:255], v[254:255], 0, s[52:53]
	global_load_lds_dwordx4 v[254:255], off
.Lbe2_3:
	v_lshl_add_u64 v[236:237], s[40:41], 0, v[134:135]
	s_mov_b32 m0, s29
	s_nop 0
	s_cmp_lg_u32 s32, 0
	s_cbranch_scc1 .Lbt2_4
	global_load_lds_dwordx4 v[236:237], off
	s_branch .Lbe2_4
.Lbt2_4:
	v_lshl_add_u64 v[252:253], v[252:253], 0, s[100:101]
	global_load_lds_dwordx4 v[252:253], off
.Lbe2_4:
	s_mov_b32 m0, s55
	s_nop 0
	s_cmp_lg_u32 s32, 0
	s_cbranch_scc1 .Lbt2_5
	global_load_lds_dwordx4 v[238:239], off
	s_branch .Lbe2_5
.Lbt2_5:
	v_lshl_add_u64 v[254:255], v[254:255], 0, s[100:101]
	global_load_lds_dwordx4 v[254:255], off
.Lbe2_5:
	s_waitcnt vmcnt(8)
	s_waitcnt lgkmcnt(0)
	s_barrier
	s_setprio 1
	s_waitcnt lgkmcnt(0)
	v_mfma_f32_16x16x32_bf16 v[52:55], v[146:149], v[194:197], v[52:55]
	v_mfma_f32_16x16x32_bf16 v[60:63], v[170:173], v[194:197], v[60:63]
	v_mfma_f32_16x16x32_bf16 v[36:39], v[146:149], v[212:215], v[36:39]
	v_mfma_f32_16x16x32_bf16 v[44:47], v[170:173], v[212:215], v[44:47]
	v_mfma_f32_16x16x32_bf16 v[20:23], v[146:149], v[220:223], v[20:23]
	v_mfma_f32_16x16x32_bf16 v[28:31], v[170:173], v[220:223], v[28:31]
	v_mfma_f32_16x16x32_bf16 v[4:7], v[146:149], v[228:231], v[4:7]
	v_mfma_f32_16x16x32_bf16 v[12:15], v[170:173], v[228:231], v[12:15]
	v_mfma_f32_16x16x32_bf16 v[52:55], v[162:165], v[198:201], v[52:55]
	v_mfma_f32_16x16x32_bf16 v[60:63], v[174:177], v[198:201], v[60:63]
	v_mfma_f32_16x16x32_bf16 v[36:39], v[162:165], v[216:219], v[36:39]
	v_mfma_f32_16x16x32_bf16 v[44:47], v[174:177], v[216:219], v[44:47]
	v_mfma_f32_16x16x32_bf16 v[20:23], v[162:165], v[224:227], v[20:23]
	v_mfma_f32_16x16x32_bf16 v[28:31], v[174:177], v[224:227], v[28:31]
	v_mfma_f32_16x16x32_bf16 v[4:7], v[162:165], v[232:235], v[4:7]
	v_mfma_f32_16x16x32_bf16 v[12:15], v[174:177], v[232:235], v[12:15]
	s_setprio 0
	s_setprio 1
	v_mfma_f32_16x16x32_bf16 v[56:59], v[178:181], v[194:197], v[56:59]
	v_mfma_f32_16x16x32_bf16 v[64:67], v[186:189], v[194:197], v[64:67]
	v_mfma_f32_16x16x32_bf16 v[40:43], v[178:181], v[212:215], v[40:43]
	v_mfma_f32_16x16x32_bf16 v[48:51], v[186:189], v[212:215], v[48:51]
	v_mfma_f32_16x16x32_bf16 v[24:27], v[178:181], v[220:223], v[24:27]
	v_mfma_f32_16x16x32_bf16 v[32:35], v[186:189], v[220:223], v[32:35]
	v_mfma_f32_16x16x32_bf16 v[8:11], v[178:181], v[228:231], v[8:11]
	v_mfma_f32_16x16x32_bf16 v[16:19], v[186:189], v[228:231], v[16:19]
	v_mfma_f32_16x16x32_bf16 v[56:59], v[182:185], v[198:201], v[56:59]
	v_mfma_f32_16x16x32_bf16 v[64:67], v[190:193], v[198:201], v[64:67]
	v_mfma_f32_16x16x32_bf16 v[40:43], v[182:185], v[216:219], v[40:43]
	v_mfma_f32_16x16x32_bf16 v[48:51], v[190:193], v[216:219], v[48:51]
	v_mfma_f32_16x16x32_bf16 v[24:27], v[182:185], v[224:227], v[24:27]
	v_mfma_f32_16x16x32_bf16 v[32:35], v[190:193], v[224:227], v[32:35]
	v_mfma_f32_16x16x32_bf16 v[8:11], v[182:185], v[232:235], v[8:11]
	v_mfma_f32_16x16x32_bf16 v[16:19], v[190:193], v[232:235], v[16:19]
	s_setprio 0
	s_barrier
	s_add_i32 s81, 0, 0x18000
	v_add_u32_e32 v161, s81, v158
	s_add_i32 s82, 0, 0x1c000
	ds_read_b128 v[146:149], v161
	ds_read_b128 v[162:165], v161 offset:1024
	ds_read_b128 v[170:173], v161 offset:2048
	ds_read_b128 v[174:177], v161 offset:3072
	v_add_u32_e32 v161, s82, v158
	ds_read_b128 v[178:181], v161
	ds_read_b128 v[182:185], v161 offset:1024
	ds_read_b128 v[186:189], v161 offset:2048
	ds_read_b128 v[190:193], v161 offset:3072
	s_add_u32 s40, s40, 0x40000
	s_addc_u32 s41, s41, 0
	s_mov_b32 m0, s62
	v_lshl_add_u64 v[240:241], s[40:41], 0, v[134:135]
	ds_read_b128 v[194:197], v160 offset:32768
	ds_read_b128 v[198:201], v160 offset:33792
	ds_read_b128 v[212:215], v160 offset:34816
	ds_read_b128 v[216:219], v160 offset:35840
	ds_read_b128 v[220:223], v160 offset:36864
	ds_read_b128 v[224:227], v160 offset:37888
	ds_read_b128 v[228:231], v160 offset:38912
	ds_read_b128 v[232:235], v160 offset:39936
	s_cmp_lg_u32 s32, 0
	s_cbranch_scc1 .Lbt2_6
	global_load_lds_dwordx4 v[240:241], off
	s_branch .Lbe2_6

; #define PG8_STAGE(bufoff, gbase, voff) do { _Pragma("unroll") for (int _i = 0; _i < 2; ++_i) \
;         __builtin_amdgcn_global_load_lds((const unsigned*)((const char*)(gbase) + (voff)[_i]), (PG8_LAS unsigned*)(lds + (bufoff) + ldsw + _i * 8192), 16, 0, 0); } while (0)
; #define PG8_LDA(dst, b, h) do { _Pragma("unroll") for (int m = 0; m < 4; ++m) _Pragma("unroll") for (int k = 0; k < 2; ++k) dst[m][k] = *(const PG8_LAS bf16x8*)(lds + PG8_SA(b, h) + aoff + m * 2048 + k * 1024); } while (0)
; #define PG8_LDB(dst, b, h) do { _Pragma("unroll") for (int n = 0; n < 2; ++n) _Pragma("unroll") for (int k = 0; k < 2; ++k) dst[n][k] = *(const PG8_LAS bf16x8*)(lds + PG8_SB(b, h) + boff + n * 2048 + k * 1024); } while (0)
; #define PG8_MMA(ai, bj, At, Bt) do { __builtin_amdgcn_s_setprio(1); _Pragma("unroll") for (int m = 0; m < 4; ++m) _Pragma("unroll") for (int n = 0; n < 2; ++n) _Pragma("unroll") for (int k = 0; k < 2; ++k) \
;         acc[ai][bj][m][n] = __builtin_amdgcn_mfma_f32_16x16x32_bf16(Bt[n][k], At[m][k], acc[ai][bj][m][n], 0, 0, 0); __builtin_amdgcn_s_setprio(0); } while (0)
; #define PG8_WAIT_V(n) asm volatile("s_waitcnt vmcnt(" #n ")" ::: "memory")
; #define PG8_WAIT_L(n) asm volatile("s_waitcnt lgkmcnt(" #n ")" ::: "memory")
; #define PG8_BAR __builtin_amdgcn_s_barrier()
; #define PG8_SCHED __builtin_amdgcn_sched_barrier(0)
; template <class Epi, class Sched, bool ALIGN_EPI = false, bool SP2 = false>
; __device__ __forceinline__ void gemm_phase(PG8_LAS unsigned char* lds, const Gemm g, const Sched& S, const Epi& E, const int tid) {
;     ...
;             PG8_LDB(B0, 1, 0); PG8_LDB(B1, 1, 1); PG8_SCHED; PG8_LDA(At, 1, 0); PG8_STAGE(PG8_SA(0, 1), a2 + hstep, voffA);
;             PG8_WAIT_V(8); PG8_WAIT_L(0); PG8_BAR; PG8_MMA(0, 0, At, B0); PG8_MMA(0, 1, At, B1); PG8_BAR; PG8_SCHED;
.Lbe2_6:
	v_lshl_add_u64 v[240:241], s[40:41], 0, v[138:139]
	s_mov_b32 m0, s63
	s_nop 0
	s_cmp_lg_u32 s32, 0
	s_cbranch_scc1 .Lbt2_7
	global_load_lds_dwordx4 v[240:241], off
	s_branch .Lbe2_7

; #define PG8_STAGE(bufoff, gbase, voff) do { _Pragma("unroll") for (int _i = 0; _i < 2; ++_i) \
;         __builtin_amdgcn_global_load_lds((const unsigned*)((const char*)(gbase) + (voff)[_i]), (PG8_LAS unsigned*)(lds + (bufoff) + ldsw + _i * 8192), 16, 0, 0); } while (0)
; #define PG8_LDA(dst, b, h) do { _Pragma("unroll") for (int m = 0; m < 4; ++m) _Pragma("unroll") for (int k = 0; k < 2; ++k) dst[m][k] = *(const PG8_LAS bf16x8*)(lds + PG8_SA(b, h) + aoff + m * 2048 + k * 1024); } while (0)
; #define PG8_MMA(ai, bj, At, Bt) do { __builtin_amdgcn_s_setprio(1); _Pragma("unroll") for (int m = 0; m < 4; ++m) _Pragma("unroll") for (int n = 0; n < 2; ++n) _Pragma("unroll") for (int k = 0; k < 2; ++k) \
;         acc[ai][bj][m][n] = __builtin_amdgcn_mfma_f32_16x16x32_bf16(Bt[n][k], At[m][k], acc[ai][bj][m][n], 0, 0, 0); __builtin_amdgcn_s_setprio(0); } while (0)
; #define PG8_WAIT_V(n) asm volatile("s_waitcnt vmcnt(" #n ")" ::: "memory")
; #define PG8_WAIT_L(n) asm volatile("s_waitcnt lgkmcnt(" #n ")" ::: "memory")
; #define PG8_BAR __builtin_amdgcn_s_barrier()
; #define PG8_SCHED __builtin_amdgcn_sched_barrier(0)
; template <class Epi, class Sched, bool ALIGN_EPI = false, bool SP2 = false>
; __device__ __forceinline__ void gemm_phase(PG8_LAS unsigned char* lds, const Gemm g, const Sched& S, const Epi& E, const int tid) {
;     ...
;             PG8_WAIT_V(8); PG8_WAIT_L(0); PG8_BAR; PG8_MMA(0, 0, At, B0); PG8_MMA(0, 1, At, B1); PG8_BAR; PG8_SCHED;
;             PG8_LDA(At, 1, 1); PG8_STAGE(PG8_SB(1, 0), b3, voffB); PG8_STAGE(PG8_SB(1, 1), b3 + hstepB, voffB); PG8_STAGE(PG8_SA(1, 0), a3, voffA);
.Lbe2_7:
	s_waitcnt vmcnt(8)
	s_waitcnt lgkmcnt(0)
	s_barrier
	s_setprio 1
	s_waitcnt lgkmcnt(0)
	v_mfma_f32_16x16x32_bf16 v[120:123], v[146:149], v[194:197], v[120:123]
	v_mfma_f32_16x16x32_bf16 v[128:131], v[170:173], v[194:197], v[128:131]
	v_mfma_f32_16x16x32_bf16 v[100:103], v[146:149], v[212:215], v[100:103]
	v_mfma_f32_16x16x32_bf16 v[108:111], v[170:173], v[212:215], v[108:111]
	v_mfma_f32_16x16x32_bf16 v[84:87], v[146:149], v[220:223], v[84:87]
	v_mfma_f32_16x16x32_bf16 v[92:95], v[170:173], v[220:223], v[92:95]
	v_mfma_f32_16x16x32_bf16 v[68:71], v[146:149], v[228:231], v[68:71]
	v_mfma_f32_16x16x32_bf16 v[76:79], v[170:173], v[228:231], v[76:79]
	v_mfma_f32_16x16x32_bf16 v[120:123], v[162:165], v[198:201], v[120:123]
	v_mfma_f32_16x16x32_bf16 v[128:131], v[174:177], v[198:201], v[128:131]
	v_mfma_f32_16x16x32_bf16 v[100:103], v[162:165], v[216:219], v[100:103]
	v_mfma_f32_16x16x32_bf16 v[108:111], v[174:177], v[216:219], v[108:111]
	v_mfma_f32_16x16x32_bf16 v[84:87], v[162:165], v[224:227], v[84:87]
	v_mfma_f32_16x16x32_bf16 v[92:95], v[174:177], v[224:227], v[92:95]
	v_mfma_f32_16x16x32_bf16 v[68:71], v[162:165], v[232:235], v[68:71]
	v_mfma_f32_16x16x32_bf16 v[76:79], v[174:177], v[232:235], v[76:79]
	s_setprio 0
	s_setprio 1
	v_mfma_f32_16x16x32_bf16 v[116:119], v[178:181], v[194:197], v[116:119]
	v_mfma_f32_16x16x32_bf16 v[124:127], v[186:189], v[194:197], v[124:127]
	v_mfma_f32_16x16x32_bf16 v[104:107], v[178:181], v[212:215], v[104:107]
	v_mfma_f32_16x16x32_bf16 v[112:115], v[186:189], v[212:215], v[112:115]
	v_mfma_f32_16x16x32_bf16 v[88:91], v[178:181], v[220:223], v[88:91]
	v_mfma_f32_16x16x32_bf16 v[96:99], v[186:189], v[220:223], v[96:99]
	v_mfma_f32_16x16x32_bf16 v[72:75], v[178:181], v[228:231], v[72:75]
	v_mfma_f32_16x16x32_bf16 v[80:83], v[186:189], v[228:231], v[80:83]
	v_mfma_f32_16x16x32_bf16 v[116:119], v[182:185], v[198:201], v[116:119]
	v_mfma_f32_16x16x32_bf16 v[124:127], v[190:193], v[198:201], v[124:127]
	v_mfma_f32_16x16x32_bf16 v[104:107], v[182:185], v[216:219], v[104:107]
	v_mfma_f32_16x16x32_bf16 v[112:115], v[190:193], v[216:219], v[112:115]
	v_mfma_f32_16x16x32_bf16 v[88:91], v[182:185], v[224:227], v[88:91]
	v_mfma_f32_16x16x32_bf16 v[96:99], v[190:193], v[224:227], v[96:99]
	v_mfma_f32_16x16x32_bf16 v[72:75], v[182:185], v[232:235], v[72:75]
	v_mfma_f32_16x16x32_bf16 v[80:83], v[190:193], v[232:235], v[80:83]
	s_setprio 0
	s_barrier
	s_add_i32 s40, s81, s43
	v_lshl_add_u64 v[150:151], v[150:151], 0, s[52:53]
	s_mov_b32 m0, s40
	ds_read_b128 v[194:197], v160 offset:49152
	ds_read_b128 v[198:201], v160 offset:50176
	ds_read_b128 v[212:215], v160 offset:51200
	ds_read_b128 v[216:219], v160 offset:52224
	ds_read_b128 v[220:223], v160 offset:53248
	ds_read_b128 v[224:227], v160 offset:54272
	ds_read_b128 v[228:231], v160 offset:55296
	ds_read_b128 v[232:235], v160 offset:56320
	s_cmp_lg_u32 s32, 0
	s_cbranch_scc1 .Lbt2_8
	global_load_lds_dwordx4 v[150:151], off

; #define PG8_STAGE(bufoff, gbase, voff) do { _Pragma("unroll") for (int _i = 0; _i < 2; ++_i) \
;         __builtin_amdgcn_global_load_lds((const unsigned*)((const char*)(gbase) + (voff)[_i]), (PG8_LAS unsigned*)(lds + (bufoff) + ldsw + _i * 8192), 16, 0, 0); } while (0)
; #define PG8_LDA(dst, b, h) do { _Pragma("unroll") for (int m = 0; m < 4; ++m) _Pragma("unroll") for (int k = 0; k < 2; ++k) dst[m][k] = *(const PG8_LAS bf16x8*)(lds + PG8_SA(b, h) + aoff + m * 2048 + k * 1024); } while (0)
; template <class Epi, class Sched, bool ALIGN_EPI = false, bool SP2 = false>
; __device__ __forceinline__ void gemm_phase(PG8_LAS unsigned char* lds, const Gemm g, const Sched& S, const Epi& E, const int tid) {
;     ...
;             PG8_LDA(At, 1, 1); PG8_STAGE(PG8_SB(1, 0), b3, voffB); PG8_STAGE(PG8_SB(1, 1), b3 + hstepB, voffB); PG8_STAGE(PG8_SA(1, 0), a3, voffA);
.Lbt2_11:
	v_lshl_add_u64 v[150:151], v[236:237], 0, s[52:53]
	s_mov_b32 m0, s64
	s_nop 0
	s_cmp_lg_u32 s32, 0
	s_cbranch_scc1 .Lbt2_12
	global_load_lds_dwordx4 v[150:151], off
	s_branch .Lbe2_12

; #define PG8_STAGE(bufoff, gbase, voff) do { _Pragma("unroll") for (int _i = 0; _i < 2; ++_i) \
;         __builtin_amdgcn_global_load_lds((const unsigned*)((const char*)(gbase) + (voff)[_i]), (PG8_LAS unsigned*)(lds + (bufoff) + ldsw + _i * 8192), 16, 0, 0); } while (0)
; #define PG8_LDA(dst, b, h) do { _Pragma("unroll") for (int m = 0; m < 4; ++m) _Pragma("unroll") for (int k = 0; k < 2; ++k) dst[m][k] = *(const PG8_LAS bf16x8*)(lds + PG8_SA(b, h) + aoff + m * 2048 + k * 1024); } while (0)
; template <class Epi, class Sched, bool ALIGN_EPI = false, bool SP2 = false>
; __device__ __forceinline__ void gemm_phase(PG8_LAS unsigned char* lds, const Gemm g, const Sched& S, const Epi& E, const int tid) {
;     ...
;             PG8_LDA(At, 1, 1); PG8_STAGE(PG8_SB(1, 0), b3, voffB); PG8_STAGE(PG8_SB(1, 1), b3 + hstepB, voffB); PG8_STAGE(PG8_SA(1, 0), a3, voffA);
.Lbe2_12:
	v_lshl_add_u64 v[150:151], v[238:239], 0, s[52:53]
	s_mov_b32 m0, s65
	s_nop 0
	s_cmp_lg_u32 s32, 0
	s_cbranch_scc1 .Lbt2_13
	global_load_lds_dwordx4 v[150:151], off
	s_branch .Lbe2_13

; template <int RA, int NP, int NS, int KT, class R8>
; DI void small_gemm(LAS unsigned char* lds, const bf16* __restrict__ A, const bf16* __restrict__ Bt, int K, int row_base, int col_base, const R8& e, int tid, int wave, int lane) {
;     ...
;     for (int s = 0; s < NS - 1; ++s) SG_STAGE(s, s);
.LBB0_982:
	s_cmp_lg_u32 s32, 0
	s_cbranch_scc0 .Leh2_e
	v_lshl_add_u64 v[252:253], v[252:253], 0, s[52:53]
	v_lshl_add_u64 v[254:255], v[254:255], 0, s[52:53]
	s_add_i32 m0, s29, 0xc000
	s_nop 0
	global_load_lds_dwordx4 v[252:253], off
	s_add_i32 m0, s29, 0xe000
	s_nop 0
	global_load_lds_dwordx4 v[254:255], off

; template <class Epi, class Sched, bool ALIGN_EPI = false, bool SP2 = false>
; __device__ __forceinline__ void gemm_phase(PG8_LAS unsigned char* lds, const Gemm g, const Sched& S, const Epi& E, const int tid) {
;     ...
;         const bool has_next = S.next(ui + 1, nxt);
;         const char* nA = has_next ? (const char*)g.A + (size_t)nxt.pm * tstep : cA; const char* nB = has_next ? (const char*)g.Bt + (size_t)nxt.pn * tstep : cB;
;         for (int t = 0; t < nt; t += 2) {
;             const bool last = (t == nt - 2);
;             const char* a1 = cA + (size_t)(t + 1) * kstep;
;             const char* a2 = last ? nA : cA + (size_t)(t + 2) * kstep; const char* b2 = last ? nB : cB + (size_t)(t + 2) * kstep;
;             const char* a3 = a2 + kstep; const char* b3 = b2 + kstep;
;             if (last && has_next) S.a_ready(nxt);
;             if constexpr (SP2) {
;             PG8_LDB(B0, 0, 0); PG8_LDB(B1, 0, 1); PG8_SCHED; PG8_LDA(At, 0, 0); PG8_STAGE(PG8_SA(1, 1), a1 + hstep, voffA);
;             PG8_WAIT_V(8); PG8_WAIT_L(0); PG8_BAR; PG8_MMA(0, 0, At, B0); PG8_MMA(0, 1, At, B1); PG8_BAR; PG8_SCHED;
;             PG8_LDA(At, 0, 1); PG8_STAGE(PG8_SB(0, 0), b2, voffB); PG8_STAGE(PG8_SB(0, 1), b2 + hstepB, voffB); PG8_STAGE(PG8_SA(0, 0), a2, voffA);
;             PG8_WAIT_V(8); PG8_WAIT_L(0); PG8_BAR; PG8_MMA(1, 0, At, B0); PG8_MMA(1, 1, At, B1); PG8_BAR; PG8_SCHED;
; template <int RA, int NP, int NS, int KT, class R8>
; DI void small_gemm(LAS unsigned char* lds, const bf16* __restrict__ A, const bf16* __restrict__ Bt, int K, int row_base, int col_base, const R8& e, int tid, int wave, int lane) {
;     ...
;     int R, Cc; pg8::stage_rc(tid * 16, R, Cc);
;     const int Rb = (R & ~31) + pg8::perm32(R & 31);
;     const bf16* asrc = A + (size_t)(row_base + R) * K + Cc;
;     const bf16* bsrc = Bt + (size_t)(col_base + Rb) * K + Cc;
;     const size_t bgrp = (size_t)64 * K;
;     const int NT = K / (64 * KT);
;     ...
;     const int r0 = row_base + 16 * (wr * RA), c0 = col_base + wc * (32 * NP);
;     float rsv[RA]; u32x4 prew[RA][NP];
; #pragma unroll
;     for (int ra = 0; ra < RA; ++ra) { rsv[ra] = 1.f; if constexpr (R8::NEED_RS) rsv[ra] = pg8::rs_of_row(e.SS, r0 + 16 * ra + fr, fq);
; #pragma unroll
;         for (int np = 0; np < NP; ++np) { prew[ra][np] = (u32x4){0u, 0u, 0u, 0u}; if constexpr (R8::HAS_PRE) prew[ra][np] = e.pre(r0 + 16 * ra + fr, c0 + 32 * np + 8 * fq); } }
.LBB0_1108:
	s_add_u32 s42, s40, 0xfffc0080
	s_addc_u32 s43, s41, -1
	s_add_i32 s84, 0, 0x10000
	s_cmp_eq_u32 s83, 12
	s_cselect_b32 s55, s23, s43
	s_cselect_b32 s54, s79, s42
	v_add_u32_e32 v163, s84, v157
	s_cselect_b32 s43, s21, s82
	s_cselect_b32 s42, s80, s81
	s_cmp_eq_u32 s83, 12
	s_cselect_b32 s32, 1, 0
	s_andn2_b32 s32, s32, s28
	s_cmp_lg_u32 s32, 0
	s_cbranch_scc0 .Leh3_t
	s_lshl_b32 s92, s62, 6
	s_lshl_b32 s93, s3, 7
	s_and_b32 s92, s92, 64
	s_or_b32 s93, s92, s93
	s_or_b32 s98, s93, 0x4000
	s_lshl_b32 s93, s27, 2
	v_add_u32_e32 v212, s98, v133
	s_and_b32 s92, s93, 0xffffffc0
	v_ashrrev_i32_e32 v213, 31, v212
	v_and_b32_e32 v214, 0xffffffe0, v133
	v_lshlrev_b64 v[220:221], 11, v[212:213]
	v_or_b32_e32 v212, s92, v154
	v_and_b32_e32 v215, 24, v155
	v_add_u32_e32 v212, v212, v214
	s_ashr_i32 s99, s34, 6
	s_lshr_b32 s55, s34, 31
	v_or3_b32 v212, v212, v215, v153
	s_add_i32 s55, s99, s55
	v_ashrrev_i32_e32 v213, 31, v212
	s_ashr_i32 s54, s55, 1
	v_lshlrev_b64 v[212:213], 11, v[212:213]
	v_lshl_add_u64 v[222:223], s[12:13], 0, v[212:213]
	s_lshl_b32 s43, s54, 4
	s_add_i32 s98, s98, s43
	v_or_b32_e32 v228, s98, v152
	v_ashrrev_i32_e32 v229, 31, v228
	v_lshlrev_b64 v[212:213], 7, v[228:229]
	v_mov_b32_e32 v234, v132
	v_ashrrev_i32_e32 v235, 31, v132
	v_lshl_add_u64 v[212:213], s[4:5], 0, v[212:213]
	s_lshl_b32 s42, s99, 10
	v_lshlrev_b32_e32 v214, 2, v151
	v_mov_b32_e32 v215, v2
	v_lshl_add_u64 v[220:221], s[8:9], 0, v[220:221]
	v_lshlrev_b64 v[224:225], 1, v[234:235]
	s_add_i32 s42, s42, 0
	v_lshl_add_u64 v[216:217], v[212:213], 0, v[214:215]
	v_lshl_add_u64 v[232:233], v[220:221], 0, v[224:225]
	v_lshl_add_u64 v[230:231], v[222:223], 0, v[224:225]
	s_mov_b32 s100, 0x200
	s_mov_b32 s101, 0
	v_lshl_add_u64 v[252:253], v[232:233], 0, s[100:101]
	v_lshl_add_u64 v[254:255], v[230:231], 0, s[100:101]
	s_mov_b32 s100, 0xfffffd80
	s_mov_b32 s101, -1
.Leh3_t:
	s_add_i32 s86, 0, 0x14000
	ds_read_b128 v[146:149], v163
	ds_read_b128 v[164:167], v163 offset:1024
	ds_read_b128 v[170:173], v163 offset:2048
	ds_read_b128 v[174:177], v163 offset:3072
	v_add_u32_e32 v163, s86, v157
	ds_read_b128 v[178:181], v163
	ds_read_b128 v[182:185], v163 offset:1024
	ds_read_b128 v[186:189], v163 offset:2048
	ds_read_b128 v[190:193], v163 offset:3072
	v_lshl_add_u64 v[236:237], s[40:41], 0, v[142:143]
	s_add_i32 m0, s37, 0xc000
	ds_read_b128 v[194:197], v162
	ds_read_b128 v[198:201], v162 offset:1024
	ds_read_b128 v[212:215], v162 offset:2048
	ds_read_b128 v[216:219], v162 offset:3072
	ds_read_b128 v[220:223], v162 offset:4096
	ds_read_b128 v[224:227], v162 offset:5120
	ds_read_b128 v[228:231], v162 offset:6144
	ds_read_b128 v[232:235], v162 offset:7168
	global_load_lds_dwordx4 v[236:237], off
	v_lshl_add_u64 v[236:237], s[40:41], 0, v[144:145]
	s_add_i32 m0, s37, 0xe000
	s_nop 0
	global_load_lds_dwordx4 v[236:237], off
	s_waitcnt vmcnt(8)
	s_waitcnt lgkmcnt(0)
	s_barrier
	s_setprio 1
	s_waitcnt lgkmcnt(0)
	v_mfma_f32_16x16x32_bf16 v[128:131], v[146:149], v[194:197], v[128:131]
	v_mfma_f32_16x16x32_bf16 v[124:127], v[170:173], v[194:197], v[124:127]
	v_mfma_f32_16x16x32_bf16 v[112:115], v[146:149], v[212:215], v[112:115]
	v_mfma_f32_16x16x32_bf16 v[108:111], v[170:173], v[212:215], v[108:111]
	v_mfma_f32_16x16x32_bf16 v[96:99], v[146:149], v[220:223], v[96:99]
	v_mfma_f32_16x16x32_bf16 v[92:95], v[170:173], v[220:223], v[92:95]
	v_mfma_f32_16x16x32_bf16 v[80:83], v[146:149], v[228:231], v[80:83]
	v_mfma_f32_16x16x32_bf16 v[76:79], v[170:173], v[228:231], v[76:79]
	v_mfma_f32_16x16x32_bf16 v[128:131], v[164:167], v[198:201], v[128:131]
	v_mfma_f32_16x16x32_bf16 v[124:127], v[174:177], v[198:201], v[124:127]
	v_mfma_f32_16x16x32_bf16 v[112:115], v[164:167], v[216:219], v[112:115]
	v_mfma_f32_16x16x32_bf16 v[108:111], v[174:177], v[216:219], v[108:111]
	v_mfma_f32_16x16x32_bf16 v[96:99], v[164:167], v[224:227], v[96:99]
	v_mfma_f32_16x16x32_bf16 v[92:95], v[174:177], v[224:227], v[92:95]
	v_mfma_f32_16x16x32_bf16 v[80:83], v[164:167], v[232:235], v[80:83]
	v_mfma_f32_16x16x32_bf16 v[76:79], v[174:177], v[232:235], v[76:79]
	s_setprio 0
	s_setprio 1
	v_mfma_f32_16x16x32_bf16 v[120:123], v[178:181], v[194:197], v[120:123]
	v_mfma_f32_16x16x32_bf16 v[116:119], v[186:189], v[194:197], v[116:119]
	v_mfma_f32_16x16x32_bf16 v[104:107], v[178:181], v[212:215], v[104:107]
	v_mfma_f32_16x16x32_bf16 v[100:103], v[186:189], v[212:215], v[100:103]
	v_mfma_f32_16x16x32_bf16 v[88:91], v[178:181], v[220:223], v[88:91]
	v_mfma_f32_16x16x32_bf16 v[84:87], v[186:189], v[220:223], v[84:87]
	v_mfma_f32_16x16x32_bf16 v[72:75], v[178:181], v[228:231], v[72:75]
	v_mfma_f32_16x16x32_bf16 v[68:71], v[186:189], v[228:231], v[68:71]
	v_mfma_f32_16x16x32_bf16 v[120:123], v[182:185], v[198:201], v[120:123]
	v_mfma_f32_16x16x32_bf16 v[116:119], v[190:193], v[198:201], v[116:119]
	v_mfma_f32_16x16x32_bf16 v[104:107], v[182:185], v[216:219], v[104:107]
	v_mfma_f32_16x16x32_bf16 v[100:103], v[190:193], v[216:219], v[100:103]
	v_mfma_f32_16x16x32_bf16 v[88:91], v[182:185], v[224:227], v[88:91]
	v_mfma_f32_16x16x32_bf16 v[84:87], v[190:193], v[224:227], v[84:87]
	v_mfma_f32_16x16x32_bf16 v[72:75], v[182:185], v[232:235], v[72:75]
	v_mfma_f32_16x16x32_bf16 v[68:71], v[190:193], v[232:235], v[68:71]
	s_setprio 0
	s_barrier
	s_add_i32 s84, s84, s63
	v_lshl_add_u64 v[236:237], s[42:43], 0, v[138:139]
	s_mov_b32 m0, s84
	ds_read_b128 v[194:197], v162 offset:16384
	ds_read_b128 v[198:201], v162 offset:17408
	ds_read_b128 v[212:215], v162 offset:18432
	ds_read_b128 v[216:219], v162 offset:19456
	ds_read_b128 v[220:223], v162 offset:20480
	ds_read_b128 v[224:227], v162 offset:21504
	ds_read_b128 v[228:231], v162 offset:22528
	ds_read_b128 v[232:235], v162 offset:23552
	s_cmp_lg_u32 s32, 0
	s_cbranch_scc1 .Lbt3_0
	global_load_lds_dwordx4 v[236:237], off
	s_branch .Lbe3_0

; #define PG8_STAGE(bufoff, gbase, voff) do { _Pragma("unroll") for (int _i = 0; _i < 2; ++_i) \
;         __builtin_amdgcn_global_load_lds((const unsigned*)((const char*)(gbase) + (voff)[_i]), (PG8_LAS unsigned*)(lds + (bufoff) + ldsw + _i * 8192), 16, 0, 0); } while (0)
; #define PG8_LDA(dst, b, h) do { _Pragma("unroll") for (int m = 0; m < 4; ++m) _Pragma("unroll") for (int k = 0; k < 2; ++k) dst[m][k] = *(const PG8_LAS bf16x8*)(lds + PG8_SA(b, h) + aoff + m * 2048 + k * 1024); } while (0)
; template <class Epi, class Sched, bool ALIGN_EPI = false, bool SP2 = false>
; __device__ __forceinline__ void gemm_phase(PG8_LAS unsigned char* lds, const Gemm g, const Sched& S, const Epi& E, const int tid) {
;     ...
;             PG8_LDA(At, 0, 1); PG8_STAGE(PG8_SB(0, 0), b2, voffB); PG8_STAGE(PG8_SB(0, 1), b2 + hstepB, voffB); PG8_STAGE(PG8_SA(0, 0), a2, voffA);
.Lbe3_0:
	s_add_i32 m0, s84, 0x2000
	s_add_u32 s84, s42, 0x10000
	v_lshl_add_u64 v[238:239], s[42:43], 0, v[134:135]
	s_addc_u32 s85, s43, 0
	s_add_i32 s86, s86, s63
	s_cmp_lg_u32 s32, 0
	s_cbranch_scc1 .Lbt3_1
	global_load_lds_dwordx4 v[238:239], off
	s_branch .Lbe3_1

; #define PG8_STAGE(bufoff, gbase, voff) do { _Pragma("unroll") for (int _i = 0; _i < 2; ++_i) \
;         __builtin_amdgcn_global_load_lds((const unsigned*)((const char*)(gbase) + (voff)[_i]), (PG8_LAS unsigned*)(lds + (bufoff) + ldsw + _i * 8192), 16, 0, 0); } while (0)
; #define PG8_LDA(dst, b, h) do { _Pragma("unroll") for (int m = 0; m < 4; ++m) _Pragma("unroll") for (int k = 0; k < 2; ++k) dst[m][k] = *(const PG8_LAS bf16x8*)(lds + PG8_SA(b, h) + aoff + m * 2048 + k * 1024); } while (0)
; template <class Epi, class Sched, bool ALIGN_EPI = false, bool SP2 = false>
; __device__ __forceinline__ void gemm_phase(PG8_LAS unsigned char* lds, const Gemm g, const Sched& S, const Epi& E, const int tid) {
;     ...
;             PG8_LDA(At, 0, 1); PG8_STAGE(PG8_SB(0, 0), b2, voffB); PG8_STAGE(PG8_SB(0, 1), b2 + hstepB, voffB); PG8_STAGE(PG8_SA(0, 0), a2, voffA);
.Lbe3_1:
	v_lshl_add_u64 v[240:241], s[84:85], 0, v[138:139]
	s_mov_b32 m0, s86
	v_lshl_add_u64 v[242:243], s[54:55], 0, v[136:137]
	s_cmp_lg_u32 s32, 0
	s_cbranch_scc1 .Lbt3_2
	global_load_lds_dwordx4 v[240:241], off
	s_branch .Lbe3_2

; #define PG8_STAGE(bufoff, gbase, voff) do { _Pragma("unroll") for (int _i = 0; _i < 2; ++_i) \
;         __builtin_amdgcn_global_load_lds((const unsigned*)((const char*)(gbase) + (voff)[_i]), (PG8_LAS unsigned*)(lds + (bufoff) + ldsw + _i * 8192), 16, 0, 0); } while (0)
; #define PG8_LDA(dst, b, h) do { _Pragma("unroll") for (int m = 0; m < 4; ++m) _Pragma("unroll") for (int k = 0; k < 2; ++k) dst[m][k] = *(const PG8_LAS bf16x8*)(lds + PG8_SA(b, h) + aoff + m * 2048 + k * 1024); } while (0)
; template <class Epi, class Sched, bool ALIGN_EPI = false, bool SP2 = false>
; __device__ __forceinline__ void gemm_phase(PG8_LAS unsigned char* lds, const Gemm g, const Sched& S, const Epi& E, const int tid) {
;     ...
;             PG8_LDA(At, 0, 1); PG8_STAGE(PG8_SB(0, 0), b2, voffB); PG8_STAGE(PG8_SB(0, 1), b2 + hstepB, voffB); PG8_STAGE(PG8_SA(0, 0), a2, voffA);
.Lbe3_2:
	v_lshl_add_u64 v[240:241], s[84:85], 0, v[134:135]
	s_add_i32 m0, s86, 0x2000
	s_nop 0
	s_cmp_lg_u32 s32, 0
	s_cbranch_scc1 .Lbt3_3
	global_load_lds_dwordx4 v[240:241], off
	s_branch .Lbe3_3

; #define PG8_STAGE(bufoff, gbase, voff) do { _Pragma("unroll") for (int _i = 0; _i < 2; ++_i) \
;         __builtin_amdgcn_global_load_lds((const unsigned*)((const char*)(gbase) + (voff)[_i]), (PG8_LAS unsigned*)(lds + (bufoff) + ldsw + _i * 8192), 16, 0, 0); } while (0)
; #define PG8_LDA(dst, b, h) do { _Pragma("unroll") for (int m = 0; m < 4; ++m) _Pragma("unroll") for (int k = 0; k < 2; ++k) dst[m][k] = *(const PG8_LAS bf16x8*)(lds + PG8_SA(b, h) + aoff + m * 2048 + k * 1024); } while (0)
; template <class Epi, class Sched, bool ALIGN_EPI = false, bool SP2 = false>
; __device__ __forceinline__ void gemm_phase(PG8_LAS unsigned char* lds, const Gemm g, const Sched& S, const Epi& E, const int tid) {
;     ...
;             PG8_LDA(At, 0, 1); PG8_STAGE(PG8_SB(0, 0), b2, voffB); PG8_STAGE(PG8_SB(0, 1), b2 + hstepB, voffB); PG8_STAGE(PG8_SA(0, 0), a2, voffA);
.Lbe3_3:
	v_lshl_add_u64 v[240:241], s[54:55], 0, v[140:141]
	s_mov_b32 m0, s37
	s_nop 0
	s_cmp_lg_u32 s32, 0
	s_cbranch_scc1 .Lbt3_4
	global_load_lds_dwordx4 v[240:241], off
	s_branch .Lbe3_4

; #define PG8_STAGE(bufoff, gbase, voff) do { _Pragma("unroll") for (int _i = 0; _i < 2; ++_i) \
;         __builtin_amdgcn_global_load_lds((const unsigned*)((const char*)(gbase) + (voff)[_i]), (PG8_LAS unsigned*)(lds + (bufoff) + ldsw + _i * 8192), 16, 0, 0); } while (0)
; #define PG8_LDA(dst, b, h) do { _Pragma("unroll") for (int m = 0; m < 4; ++m) _Pragma("unroll") for (int k = 0; k < 2; ++k) dst[m][k] = *(const PG8_LAS bf16x8*)(lds + PG8_SA(b, h) + aoff + m * 2048 + k * 1024); } while (0)
; template <class Epi, class Sched, bool ALIGN_EPI = false, bool SP2 = false>
; __device__ __forceinline__ void gemm_phase(PG8_LAS unsigned char* lds, const Gemm g, const Sched& S, const Epi& E, const int tid) {
;     ...
;             PG8_LDA(At, 0, 1); PG8_STAGE(PG8_SB(0, 0), b2, voffB); PG8_STAGE(PG8_SB(0, 1), b2 + hstepB, voffB); PG8_STAGE(PG8_SA(0, 0), a2, voffA);
.Lbe3_4:
	s_mov_b32 m0, s39
	s_nop 0
	s_cmp_lg_u32 s32, 0
	s_cbranch_scc1 .Lbt3_5
	global_load_lds_dwordx4 v[242:243], off
	s_branch .Lbe3_5

; #define PG8_STAGE(bufoff, gbase, voff) do { _Pragma("unroll") for (int _i = 0; _i < 2; ++_i) \
;         __builtin_amdgcn_global_load_lds((const unsigned*)((const char*)(gbase) + (voff)[_i]), (PG8_LAS unsigned*)(lds + (bufoff) + ldsw + _i * 8192), 16, 0, 0); } while (0)
; #define PG8_LDA(dst, b, h) do { _Pragma("unroll") for (int m = 0; m < 4; ++m) _Pragma("unroll") for (int k = 0; k < 2; ++k) dst[m][k] = *(const PG8_LAS bf16x8*)(lds + PG8_SA(b, h) + aoff + m * 2048 + k * 1024); } while (0)
; #define PG8_LDB(dst, b, h) do { _Pragma("unroll") for (int n = 0; n < 2; ++n) _Pragma("unroll") for (int k = 0; k < 2; ++k) dst[n][k] = *(const PG8_LAS bf16x8*)(lds + PG8_SB(b, h) + boff + n * 2048 + k * 1024); } while (0)
; #define PG8_MMA(ai, bj, At, Bt) do { __builtin_amdgcn_s_setprio(1); _Pragma("unroll") for (int m = 0; m < 4; ++m) _Pragma("unroll") for (int n = 0; n < 2; ++n) _Pragma("unroll") for (int k = 0; k < 2; ++k) \
;         acc[ai][bj][m][n] = __builtin_amdgcn_mfma_f32_16x16x32_bf16(Bt[n][k], At[m][k], acc[ai][bj][m][n], 0, 0, 0); __builtin_amdgcn_s_setprio(0); } while (0)
; #define PG8_WAIT_V(n) asm volatile("s_waitcnt vmcnt(" #n ")" ::: "memory")
; #define PG8_WAIT_L(n) asm volatile("s_waitcnt lgkmcnt(" #n ")" ::: "memory")
; #define PG8_BAR __builtin_amdgcn_s_barrier()
; #define PG8_SCHED __builtin_amdgcn_sched_barrier(0)
; template <class Epi, class Sched, bool ALIGN_EPI = false, bool SP2 = false>
; __device__ __forceinline__ void gemm_phase(PG8_LAS unsigned char* lds, const Gemm g, const Sched& S, const Epi& E, const int tid) {
;     ...
;             PG8_WAIT_V(8); PG8_WAIT_L(0); PG8_BAR; PG8_MMA(1, 0, At, B0); PG8_MMA(1, 1, At, B1); PG8_BAR; PG8_SCHED;
;             PG8_LDB(B0, 1, 0); PG8_LDB(B1, 1, 1); PG8_SCHED; PG8_LDA(At, 1, 0); PG8_STAGE(PG8_SA(0, 1), a2 + hstep, voffA);
.Lbe3_5:
	s_waitcnt vmcnt(8)
	s_waitcnt lgkmcnt(0)
	s_barrier
	s_setprio 1
	s_waitcnt lgkmcnt(0)
	v_mfma_f32_16x16x32_bf16 v[64:67], v[146:149], v[194:197], v[64:67]
	v_mfma_f32_16x16x32_bf16 v[60:63], v[170:173], v[194:197], v[60:63]
	v_mfma_f32_16x16x32_bf16 v[48:51], v[146:149], v[212:215], v[48:51]
	v_mfma_f32_16x16x32_bf16 v[44:47], v[170:173], v[212:215], v[44:47]
	v_mfma_f32_16x16x32_bf16 v[32:35], v[146:149], v[220:223], v[32:35]
	v_mfma_f32_16x16x32_bf16 v[28:31], v[170:173], v[220:223], v[28:31]
	v_mfma_f32_16x16x32_bf16 v[16:19], v[146:149], v[228:231], v[16:19]
	v_mfma_f32_16x16x32_bf16 v[12:15], v[170:173], v[228:231], v[12:15]
	v_mfma_f32_16x16x32_bf16 v[64:67], v[164:167], v[198:201], v[64:67]
	v_mfma_f32_16x16x32_bf16 v[60:63], v[174:177], v[198:201], v[60:63]
	v_mfma_f32_16x16x32_bf16 v[48:51], v[164:167], v[216:219], v[48:51]
	v_mfma_f32_16x16x32_bf16 v[44:47], v[174:177], v[216:219], v[44:47]
	v_mfma_f32_16x16x32_bf16 v[32:35], v[164:167], v[224:227], v[32:35]
	v_mfma_f32_16x16x32_bf16 v[28:31], v[174:177], v[224:227], v[28:31]
	v_mfma_f32_16x16x32_bf16 v[16:19], v[164:167], v[232:235], v[16:19]
	v_mfma_f32_16x16x32_bf16 v[12:15], v[174:177], v[232:235], v[12:15]
	s_setprio 0
	s_setprio 1
	v_mfma_f32_16x16x32_bf16 v[56:59], v[178:181], v[194:197], v[56:59]
	v_mfma_f32_16x16x32_bf16 v[52:55], v[186:189], v[194:197], v[52:55]
	v_mfma_f32_16x16x32_bf16 v[40:43], v[178:181], v[212:215], v[40:43]
	v_mfma_f32_16x16x32_bf16 v[36:39], v[186:189], v[212:215], v[36:39]
	v_mfma_f32_16x16x32_bf16 v[24:27], v[178:181], v[220:223], v[24:27]
	v_mfma_f32_16x16x32_bf16 v[20:23], v[186:189], v[220:223], v[20:23]
	v_mfma_f32_16x16x32_bf16 v[8:11], v[178:181], v[228:231], v[8:11]
	v_mfma_f32_16x16x32_bf16 v[4:7], v[186:189], v[228:231], v[4:7]
	v_mfma_f32_16x16x32_bf16 v[56:59], v[182:185], v[198:201], v[56:59]
	v_mfma_f32_16x16x32_bf16 v[52:55], v[190:193], v[198:201], v[52:55]
	v_mfma_f32_16x16x32_bf16 v[40:43], v[182:185], v[216:219], v[40:43]
	v_mfma_f32_16x16x32_bf16 v[36:39], v[190:193], v[216:219], v[36:39]
	v_mfma_f32_16x16x32_bf16 v[24:27], v[182:185], v[224:227], v[24:27]
	v_mfma_f32_16x16x32_bf16 v[20:23], v[190:193], v[224:227], v[20:23]
	v_mfma_f32_16x16x32_bf16 v[8:11], v[182:185], v[232:235], v[8:11]
	v_mfma_f32_16x16x32_bf16 v[4:7], v[190:193], v[232:235], v[4:7]
	s_setprio 0
	s_barrier
	s_add_i32 s84, 0, 0x18000
	v_add_u32_e32 v163, s84, v157
	s_add_i32 s85, 0, 0x1c000
	ds_read_b128 v[146:149], v163
	ds_read_b128 v[164:167], v163 offset:1024
	ds_read_b128 v[170:173], v163 offset:2048
	ds_read_b128 v[174:177], v163 offset:3072
	v_add_u32_e32 v163, s85, v157
	ds_read_b128 v[178:181], v163
	ds_read_b128 v[182:185], v163 offset:1024
	ds_read_b128 v[186:189], v163 offset:2048
	ds_read_b128 v[190:193], v163 offset:3072
	s_add_u32 s54, s54, 0x40000
	s_addc_u32 s55, s55, 0
	s_mov_b32 m0, s65
	v_lshl_add_u64 v[244:245], s[54:55], 0, v[140:141]
	ds_read_b128 v[194:197], v162 offset:32768
	ds_read_b128 v[198:201], v162 offset:33792
	ds_read_b128 v[212:215], v162 offset:34816
	ds_read_b128 v[216:219], v162 offset:35840
	ds_read_b128 v[220:223], v162 offset:36864
	ds_read_b128 v[224:227], v162 offset:37888
	ds_read_b128 v[228:231], v162 offset:38912
	ds_read_b128 v[232:235], v162 offset:39936
	s_cmp_lg_u32 s32, 0
	s_cbranch_scc1 .Lbt3_6
	global_load_lds_dwordx4 v[244:245], off
	s_branch .Lbe3_6

; #define PG8_STAGE(bufoff, gbase, voff) do { _Pragma("unroll") for (int _i = 0; _i < 2; ++_i) \
;         __builtin_amdgcn_global_load_lds((const unsigned*)((const char*)(gbase) + (voff)[_i]), (PG8_LAS unsigned*)(lds + (bufoff) + ldsw + _i * 8192), 16, 0, 0); } while (0)
; #define PG8_LDA(dst, b, h) do { _Pragma("unroll") for (int m = 0; m < 4; ++m) _Pragma("unroll") for (int k = 0; k < 2; ++k) dst[m][k] = *(const PG8_LAS bf16x8*)(lds + PG8_SA(b, h) + aoff + m * 2048 + k * 1024); } while (0)
; #define PG8_LDB(dst, b, h) do { _Pragma("unroll") for (int n = 0; n < 2; ++n) _Pragma("unroll") for (int k = 0; k < 2; ++k) dst[n][k] = *(const PG8_LAS bf16x8*)(lds + PG8_SB(b, h) + boff + n * 2048 + k * 1024); } while (0)
; #define PG8_SCHED __builtin_amdgcn_sched_barrier(0)
; template <class Epi, class Sched, bool ALIGN_EPI = false, bool SP2 = false>
; __device__ __forceinline__ void gemm_phase(PG8_LAS unsigned char* lds, const Gemm g, const Sched& S, const Epi& E, const int tid) {
;     ...
;             PG8_LDB(B0, 1, 0); PG8_LDB(B1, 1, 1); PG8_SCHED; PG8_LDA(At, 1, 0); PG8_STAGE(PG8_SA(0, 1), a2 + hstep, voffA);
.Lbe3_6:
	v_lshl_add_u64 v[244:245], s[54:55], 0, v[136:137]
	s_mov_b32 m0, s66
	s_nop 0
	s_cmp_lg_u32 s32, 0
	s_cbranch_scc1 .Lbt3_7
	global_load_lds_dwordx4 v[244:245], off
	s_branch .Lbe3_7

; #define PG8_STAGE(bufoff, gbase, voff) do { _Pragma("unroll") for (int _i = 0; _i < 2; ++_i) \
;         __builtin_amdgcn_global_load_lds((const unsigned*)((const char*)(gbase) + (voff)[_i]), (PG8_LAS unsigned*)(lds + (bufoff) + ldsw + _i * 8192), 16, 0, 0); } while (0)
; #define PG8_LDA(dst, b, h) do { _Pragma("unroll") for (int m = 0; m < 4; ++m) _Pragma("unroll") for (int k = 0; k < 2; ++k) dst[m][k] = *(const PG8_LAS bf16x8*)(lds + PG8_SA(b, h) + aoff + m * 2048 + k * 1024); } while (0)
; #define PG8_MMA(ai, bj, At, Bt) do { __builtin_amdgcn_s_setprio(1); _Pragma("unroll") for (int m = 0; m < 4; ++m) _Pragma("unroll") for (int n = 0; n < 2; ++n) _Pragma("unroll") for (int k = 0; k < 2; ++k) \
;         acc[ai][bj][m][n] = __builtin_amdgcn_mfma_f32_16x16x32_bf16(Bt[n][k], At[m][k], acc[ai][bj][m][n], 0, 0, 0); __builtin_amdgcn_s_setprio(0); } while (0)
; #define PG8_WAIT_V(n) asm volatile("s_waitcnt vmcnt(" #n ")" ::: "memory")
; #define PG8_WAIT_L(n) asm volatile("s_waitcnt lgkmcnt(" #n ")" ::: "memory")
; #define PG8_BAR __builtin_amdgcn_s_barrier()
; #define PG8_SCHED __builtin_amdgcn_sched_barrier(0)
; template <class Epi, class Sched, bool ALIGN_EPI = false, bool SP2 = false>
; __device__ __forceinline__ void gemm_phase(PG8_LAS unsigned char* lds, const Gemm g, const Sched& S, const Epi& E, const int tid) {
;     ...
;             PG8_WAIT_V(8); PG8_WAIT_L(0); PG8_BAR; PG8_MMA(0, 0, At, B0); PG8_MMA(0, 1, At, B1); PG8_BAR; PG8_SCHED;
;             PG8_LDA(At, 1, 1); PG8_STAGE(PG8_SB(1, 0), b3, voffB); PG8_STAGE(PG8_SB(1, 1), b3 + hstepB, voffB); PG8_STAGE(PG8_SA(1, 0), a3, voffA);
.Lbe3_7:
	s_waitcnt vmcnt(8)
	s_waitcnt lgkmcnt(0)
	s_barrier
	s_setprio 1
	s_waitcnt lgkmcnt(0)
	v_mfma_f32_16x16x32_bf16 v[128:131], v[146:149], v[194:197], v[128:131]
	v_mfma_f32_16x16x32_bf16 v[124:127], v[170:173], v[194:197], v[124:127]
	v_mfma_f32_16x16x32_bf16 v[112:115], v[146:149], v[212:215], v[112:115]
	v_mfma_f32_16x16x32_bf16 v[108:111], v[170:173], v[212:215], v[108:111]
	v_mfma_f32_16x16x32_bf16 v[96:99], v[146:149], v[220:223], v[96:99]
	v_mfma_f32_16x16x32_bf16 v[92:95], v[170:173], v[220:223], v[92:95]
	v_mfma_f32_16x16x32_bf16 v[80:83], v[146:149], v[228:231], v[80:83]
	v_mfma_f32_16x16x32_bf16 v[76:79], v[170:173], v[228:231], v[76:79]
	v_mfma_f32_16x16x32_bf16 v[128:131], v[164:167], v[198:201], v[128:131]
	v_mfma_f32_16x16x32_bf16 v[124:127], v[174:177], v[198:201], v[124:127]
	v_mfma_f32_16x16x32_bf16 v[112:115], v[164:167], v[216:219], v[112:115]
	v_mfma_f32_16x16x32_bf16 v[108:111], v[174:177], v[216:219], v[108:111]
	v_mfma_f32_16x16x32_bf16 v[96:99], v[164:167], v[224:227], v[96:99]
	v_mfma_f32_16x16x32_bf16 v[92:95], v[174:177], v[224:227], v[92:95]
	v_mfma_f32_16x16x32_bf16 v[80:83], v[164:167], v[232:235], v[80:83]
	v_mfma_f32_16x16x32_bf16 v[76:79], v[174:177], v[232:235], v[76:79]
	s_setprio 0
	s_setprio 1
	v_mfma_f32_16x16x32_bf16 v[120:123], v[178:181], v[194:197], v[120:123]
	v_mfma_f32_16x16x32_bf16 v[116:119], v[186:189], v[194:197], v[116:119]
	v_mfma_f32_16x16x32_bf16 v[104:107], v[178:181], v[212:215], v[104:107]
	v_mfma_f32_16x16x32_bf16 v[100:103], v[186:189], v[212:215], v[100:103]
	v_mfma_f32_16x16x32_bf16 v[88:91], v[178:181], v[220:223], v[88:91]
	v_mfma_f32_16x16x32_bf16 v[84:87], v[186:189], v[220:223], v[84:87]
	v_mfma_f32_16x16x32_bf16 v[72:75], v[178:181], v[228:231], v[72:75]
	v_mfma_f32_16x16x32_bf16 v[68:71], v[186:189], v[228:231], v[68:71]
	v_mfma_f32_16x16x32_bf16 v[120:123], v[182:185], v[198:201], v[120:123]
	v_mfma_f32_16x16x32_bf16 v[116:119], v[190:193], v[198:201], v[116:119]
	v_mfma_f32_16x16x32_bf16 v[104:107], v[182:185], v[216:219], v[104:107]
	v_mfma_f32_16x16x32_bf16 v[100:103], v[190:193], v[216:219], v[100:103]
	v_mfma_f32_16x16x32_bf16 v[88:91], v[182:185], v[224:227], v[88:91]
	v_mfma_f32_16x16x32_bf16 v[84:87], v[190:193], v[224:227], v[84:87]
	v_mfma_f32_16x16x32_bf16 v[72:75], v[182:185], v[232:235], v[72:75]
	v_mfma_f32_16x16x32_bf16 v[68:71], v[190:193], v[232:235], v[68:71]
	s_setprio 0
	s_barrier
	s_add_i32 s54, s84, s63
	v_lshl_add_u64 v[236:237], v[236:237], 0, s[52:53]
	s_mov_b32 m0, s54
	ds_read_b128 v[194:197], v162 offset:49152
	ds_read_b128 v[198:201], v162 offset:50176
	ds_read_b128 v[212:215], v162 offset:51200
	ds_read_b128 v[216:219], v162 offset:52224
	ds_read_b128 v[220:223], v162 offset:53248
	ds_read_b128 v[224:227], v162 offset:54272
	ds_read_b128 v[228:231], v162 offset:55296
	ds_read_b128 v[232:235], v162 offset:56320
	s_cmp_lg_u32 s32, 0
	s_cbranch_scc1 .Lbt3_8
	global_load_lds_dwordx4 v[236:237], off

; #define PG8_STAGE(bufoff, gbase, voff) do { _Pragma("unroll") for (int _i = 0; _i < 2; ++_i) \
;         __builtin_amdgcn_global_load_lds((const unsigned*)((const char*)(gbase) + (voff)[_i]), (PG8_LAS unsigned*)(lds + (bufoff) + ldsw + _i * 8192), 16, 0, 0); } while (0)
; #define PG8_LDA(dst, b, h) do { _Pragma("unroll") for (int m = 0; m < 4; ++m) _Pragma("unroll") for (int k = 0; k < 2; ++k) dst[m][k] = *(const PG8_LAS bf16x8*)(lds + PG8_SA(b, h) + aoff + m * 2048 + k * 1024); } while (0)
; template <class Epi, class Sched, bool ALIGN_EPI = false, bool SP2 = false>
; __device__ __forceinline__ void gemm_phase(PG8_LAS unsigned char* lds, const Gemm g, const Sched& S, const Epi& E, const int tid) {
;     ...
;             PG8_LDA(At, 1, 1); PG8_STAGE(PG8_SB(1, 0), b3, voffB); PG8_STAGE(PG8_SB(1, 1), b3 + hstepB, voffB); PG8_STAGE(PG8_SA(1, 0), a3, voffA);
.Lbt3_11:
	v_lshl_add_u64 v[236:237], v[240:241], 0, s[52:53]
	s_mov_b32 m0, s67
	s_nop 0
	s_cmp_lg_u32 s32, 0
	s_cbranch_scc1 .Lbt3_12
	global_load_lds_dwordx4 v[236:237], off
	s_branch .Lbe3_12

; #define PG8_STAGE(bufoff, gbase, voff) do { _Pragma("unroll") for (int _i = 0; _i < 2; ++_i) \
;         __builtin_amdgcn_global_load_lds((const unsigned*)((const char*)(gbase) + (voff)[_i]), (PG8_LAS unsigned*)(lds + (bufoff) + ldsw + _i * 8192), 16, 0, 0); } while (0)
; #define PG8_LDA(dst, b, h) do { _Pragma("unroll") for (int m = 0; m < 4; ++m) _Pragma("unroll") for (int k = 0; k < 2; ++k) dst[m][k] = *(const PG8_LAS bf16x8*)(lds + PG8_SA(b, h) + aoff + m * 2048 + k * 1024); } while (0)
; template <class Epi, class Sched, bool ALIGN_EPI = false, bool SP2 = false>
; __device__ __forceinline__ void gemm_phase(PG8_LAS unsigned char* lds, const Gemm g, const Sched& S, const Epi& E, const int tid) {
;     ...
;             PG8_LDA(At, 1, 1); PG8_STAGE(PG8_SB(1, 0), b3, voffB); PG8_STAGE(PG8_SB(1, 1), b3 + hstepB, voffB); PG8_STAGE(PG8_SA(1, 0), a3, voffA);
.Lbe3_12:
	v_lshl_add_u64 v[236:237], v[242:243], 0, s[52:53]
	s_mov_b32 m0, s76
	s_nop 0
	s_cmp_lg_u32 s32, 0
	s_cbranch_scc1 .Lbt3_13
	global_load_lds_dwordx4 v[236:237], off
	s_branch .Lbe3_13

; template <int RA, int NP, int NS, int KT, class R8>
; DI void small_gemm(LAS unsigned char* lds, const bf16* __restrict__ A, const bf16* __restrict__ Bt, int K, int row_base, int col_base, const R8& e, int tid, int wave, int lane) {
;     ...
;     for (int s = 0; s < NS - 1; ++s) SG_STAGE(s, s);
.LBB0_1111:
	s_cmp_lg_u32 s32, 0
	s_cbranch_scc0 .Leh3_e
	v_lshl_add_u64 v[252:253], v[252:253], 0, s[52:53]
	v_lshl_add_u64 v[254:255], v[254:255], 0, s[52:53]
	s_add_i32 m0, s37, 0xc000
	s_nop 0
	global_load_lds_dwordx4 v[252:253], off
	s_add_i32 m0, s37, 0xe000
	s_nop 0
	global_load_lds_dwordx4 v[254:255], off

;     DI bool next(int i, Unit& u) const { const int L = i * 32 + rank; if (L >= ppg * nN) return false; u.pm = ppg * grp + (L % ppg); const int p0 = L / ppg, p1 = p0 + rot; u.pn = rev ? nN - 1 - p0 : (p1 >= nN ? p1 - nN : p1); return true; }
; #define PG8_LDA(dst, b, h) do { _Pragma("unroll") for (int m = 0; m < 4; ++m) _Pragma("unroll") for (int k = 0; k < 2; ++k) dst[m][k] = *(const PG8_LAS bf16x8*)(lds + PG8_SA(b, h) + aoff + m * 2048 + k * 1024); } while (0)
; template <class Epi, class Sched, bool ALIGN_EPI = false, bool SP2 = false>
; __device__ __forceinline__ void gemm_phase(PG8_LAS unsigned char* lds, const Gemm g, const Sched& S, const Epi& E, const int tid) {
;     ...
;         const bool has_next = S.next(ui + 1, nxt);
;         const char* nA = has_next ? (const char*)g.A + (size_t)nxt.pm * tstep : cA; const char* nB = has_next ? (const char*)g.Bt + (size_t)nxt.pn * tstep : cB;
;         for (int t = 0; t < nt; t += 2) {
;             const bool last = (t == nt - 2);
;             const char* a1 = cA + (size_t)(t + 1) * kstep;
;             const char* a2 = last ? nA : cA + (size_t)(t + 2) * kstep; const char* b2 = last ? nB : cB + (size_t)(t + 2) * kstep;
;             const char* a3 = a2 + kstep; const char* b3 = b2 + kstep;
;             if (last && has_next) S.a_ready(nxt);
;             if constexpr (SP2) {
;             PG8_LDB(B0, 0, 0); PG8_LDB(B1, 0, 1); PG8_SCHED; PG8_LDA(At, 0, 0); PG8_STAGE(PG8_SA(1, 1), a1 + hstep, voffA);
;             PG8_WAIT_V(8); PG8_WAIT_L(0); PG8_BAR; PG8_MMA(0, 0, At, B0); PG8_MMA(0, 1, At, B1); PG8_BAR; PG8_SCHED;
;             PG8_LDA(At, 0, 1); PG8_STAGE(PG8_SB(0, 0), b2, voffB); PG8_STAGE(PG8_SB(0, 1), b2 + hstepB, voffB); PG8_STAGE(PG8_SA(0, 0), a2, voffA);
;             PG8_WAIT_V(8); PG8_WAIT_L(0); PG8_BAR; PG8_MMA(1, 0, At, B0); PG8_MMA(1, 1, At, B1); PG8_BAR; PG8_SCHED;
; template <int RA, int NP, int NS, int KT, class R8>
; DI void small_gemm(LAS unsigned char* lds, const bf16* __restrict__ A, const bf16* __restrict__ Bt, int K, int row_base, int col_base, const R8& e, int tid, int wave, int lane) {
;     ...
;     int R, Cc; pg8::stage_rc(tid * 16, R, Cc);
;     const int Rb = (R & ~31) + pg8::perm32(R & 31);
;     const bf16* asrc = A + (size_t)(row_base + R) * K + Cc;
;     const bf16* bsrc = Bt + (size_t)(col_base + Rb) * K + Cc;
;     const size_t bgrp = (size_t)64 * K;
;     const int NT = K / (64 * KT);
.LBB0_1266:
	s_add_u32 s38, s40, 0xfffc0080
	s_addc_u32 s39, s41, -1
	s_add_i32 s83, 0, 0x10000
	s_cmp_eq_u32 s82, 12
	s_cselect_b32 s43, s21, s39
	s_cselect_b32 s42, s29, s38
	v_add_u32_e32 v150, s83, v158
	s_cselect_b32 s39, s19, s81
	s_cselect_b32 s38, s79, s80
	s_cmp_eq_u32 s82, 12
	s_cselect_b32 s32, 1, 0
	s_andn2_b32 s32, s32, s36
	s_cmp_lg_u32 s32, 0
	s_cbranch_scc0 .Leh4_t
	s_lshl_b32 s92, s3, 2
	s_andn2_b32 s92, s92, 63
	s_lshl_b32 s93, s34, 6
	v_and_b32_e32 v212, 0xffffffe0, v133
	v_or_b32_e32 v214, s92, v154
	s_lshl_b32 s98, s27, 7
	s_and_b32 s93, s93, 64
	v_and_b32_e32 v213, 24, v155
	v_add_u32_e32 v212, v214, v212
	s_or_b32 s98, s93, s98
	s_lshr_b32 s93, s54, 31
	v_or3_b32 v212, v212, v213, v153
	s_bitset1_b32 s98, 14
	s_add_i32 s93, s54, s93
	v_ashrrev_i32_e32 v213, 31, v212
	s_ashr_i32 s99, s93, 1
	v_add_u32_e32 v216, s98, v133
	v_lshlrev_b64 v[212:213], 11, v[212:213]
	v_ashrrev_i32_e32 v217, 31, v216
	v_lshl_add_u64 v[212:213], s[12:13], 0, v[212:213]
	s_lshl_b32 s43, s99, 4
	v_mov_b32_e32 v234, v132
	v_ashrrev_i32_e32 v235, 31, v132
	s_add_i32 s98, s98, s43
	v_lshlrev_b64 v[216:217], 11, v[216:217]
	v_lshlrev_b64 v[218:219], 1, v[234:235]
	v_or_b32_e32 v224, s98, v152
	v_lshl_add_u64 v[216:217], s[8:9], 0, v[216:217]
	s_add_i32 s98, s55, 0
	v_lshl_add_u64 v[230:231], v[216:217], 0, v[218:219]
	v_lshl_add_u64 v[228:229], v[212:213], 0, v[218:219]
	s_mov_b32 s100, 0x200
	s_mov_b32 s101, 0
	v_lshl_add_u64 v[252:253], v[230:231], 0, s[100:101]
	v_lshl_add_u64 v[254:255], v[228:229], 0, s[100:101]
	s_mov_b32 s100, 0xfffffd80
	s_mov_b32 s101, -1
.Leh4_t:
	s_add_i32 s86, 0, 0x14000
	ds_read_b128 v[146:149], v150
	ds_read_b128 v[162:165], v150 offset:1024
	ds_read_b128 v[170:173], v150 offset:2048
	ds_read_b128 v[174:177], v150 offset:3072
	v_add_u32_e32 v150, s86, v158
	ds_read_b128 v[178:181], v150
	ds_read_b128 v[182:185], v150 offset:1024
	ds_read_b128 v[186:189], v150 offset:2048
	ds_read_b128 v[190:193], v150 offset:3072
	v_lshl_add_u64 v[150:151], s[40:41], 0, v[142:143]
	s_add_i32 m0, s31, 0xc000
	ds_read_b128 v[194:197], v160
	ds_read_b128 v[198:201], v160 offset:1024
	ds_read_b128 v[212:215], v160 offset:2048
	ds_read_b128 v[216:219], v160 offset:3072
	ds_read_b128 v[220:223], v160 offset:4096
	ds_read_b128 v[224:227], v160 offset:5120
	ds_read_b128 v[228:231], v160 offset:6144
	ds_read_b128 v[232:235], v160 offset:7168
	global_load_lds_dwordx4 v[150:151], off
	v_lshl_add_u64 v[150:151], s[40:41], 0, v[144:145]
	s_add_i32 m0, s31, 0xe000
	s_nop 0
	global_load_lds_dwordx4 v[150:151], off
	s_waitcnt vmcnt(8)
	s_waitcnt lgkmcnt(0)
	s_barrier
	s_setprio 1
	s_waitcnt lgkmcnt(0)
	v_mfma_f32_16x16x32_bf16 v[120:123], v[146:149], v[194:197], v[120:123]
	v_mfma_f32_16x16x32_bf16 v[128:131], v[170:173], v[194:197], v[128:131]
	v_mfma_f32_16x16x32_bf16 v[100:103], v[146:149], v[212:215], v[100:103]
	v_mfma_f32_16x16x32_bf16 v[108:111], v[170:173], v[212:215], v[108:111]
	v_mfma_f32_16x16x32_bf16 v[84:87], v[146:149], v[220:223], v[84:87]
	v_mfma_f32_16x16x32_bf16 v[92:95], v[170:173], v[220:223], v[92:95]
	v_mfma_f32_16x16x32_bf16 v[68:71], v[146:149], v[228:231], v[68:71]
	v_mfma_f32_16x16x32_bf16 v[76:79], v[170:173], v[228:231], v[76:79]
	v_mfma_f32_16x16x32_bf16 v[120:123], v[162:165], v[198:201], v[120:123]
	v_mfma_f32_16x16x32_bf16 v[128:131], v[174:177], v[198:201], v[128:131]
	v_mfma_f32_16x16x32_bf16 v[100:103], v[162:165], v[216:219], v[100:103]
	v_mfma_f32_16x16x32_bf16 v[108:111], v[174:177], v[216:219], v[108:111]
	v_mfma_f32_16x16x32_bf16 v[84:87], v[162:165], v[224:227], v[84:87]
	v_mfma_f32_16x16x32_bf16 v[92:95], v[174:177], v[224:227], v[92:95]
	v_mfma_f32_16x16x32_bf16 v[68:71], v[162:165], v[232:235], v[68:71]
	v_mfma_f32_16x16x32_bf16 v[76:79], v[174:177], v[232:235], v[76:79]
	s_setprio 0
	s_setprio 1
	v_mfma_f32_16x16x32_bf16 v[116:119], v[178:181], v[194:197], v[116:119]
	v_mfma_f32_16x16x32_bf16 v[124:127], v[186:189], v[194:197], v[124:127]
	v_mfma_f32_16x16x32_bf16 v[104:107], v[178:181], v[212:215], v[104:107]
	v_mfma_f32_16x16x32_bf16 v[112:115], v[186:189], v[212:215], v[112:115]
	v_mfma_f32_16x16x32_bf16 v[88:91], v[178:181], v[220:223], v[88:91]
	v_mfma_f32_16x16x32_bf16 v[96:99], v[186:189], v[220:223], v[96:99]
	v_mfma_f32_16x16x32_bf16 v[72:75], v[178:181], v[228:231], v[72:75]
	v_mfma_f32_16x16x32_bf16 v[80:83], v[186:189], v[228:231], v[80:83]
	v_mfma_f32_16x16x32_bf16 v[116:119], v[182:185], v[198:201], v[116:119]
	v_mfma_f32_16x16x32_bf16 v[124:127], v[190:193], v[198:201], v[124:127]
	v_mfma_f32_16x16x32_bf16 v[104:107], v[182:185], v[216:219], v[104:107]
	v_mfma_f32_16x16x32_bf16 v[112:115], v[190:193], v[216:219], v[112:115]
	v_mfma_f32_16x16x32_bf16 v[88:91], v[182:185], v[224:227], v[88:91]
	v_mfma_f32_16x16x32_bf16 v[96:99], v[190:193], v[224:227], v[96:99]
	v_mfma_f32_16x16x32_bf16 v[72:75], v[182:185], v[232:235], v[72:75]
	v_mfma_f32_16x16x32_bf16 v[80:83], v[190:193], v[232:235], v[80:83]
	s_setprio 0
	s_barrier
	s_add_i32 s83, s83, s55
	v_lshl_add_u64 v[150:151], s[38:39], 0, v[136:137]
	s_mov_b32 m0, s83
	ds_read_b128 v[194:197], v160 offset:16384
	ds_read_b128 v[198:201], v160 offset:17408
	ds_read_b128 v[212:215], v160 offset:18432
	ds_read_b128 v[216:219], v160 offset:19456
	ds_read_b128 v[220:223], v160 offset:20480
	ds_read_b128 v[224:227], v160 offset:21504
	ds_read_b128 v[228:231], v160 offset:22528
	ds_read_b128 v[232:235], v160 offset:23552
	s_cmp_lg_u32 s32, 0
	s_cbranch_scc1 .Lbt4_0
	global_load_lds_dwordx4 v[150:151], off
	s_branch .Lbe4_0

; #define PG8_STAGE(bufoff, gbase, voff) do { _Pragma("unroll") for (int _i = 0; _i < 2; ++_i) \
;         __builtin_amdgcn_global_load_lds((const unsigned*)((const char*)(gbase) + (voff)[_i]), (PG8_LAS unsigned*)(lds + (bufoff) + ldsw + _i * 8192), 16, 0, 0); } while (0)
; #define PG8_LDA(dst, b, h) do { _Pragma("unroll") for (int m = 0; m < 4; ++m) _Pragma("unroll") for (int k = 0; k < 2; ++k) dst[m][k] = *(const PG8_LAS bf16x8*)(lds + PG8_SA(b, h) + aoff + m * 2048 + k * 1024); } while (0)
; template <class Epi, class Sched, bool ALIGN_EPI = false, bool SP2 = false>
; __device__ __forceinline__ void gemm_phase(PG8_LAS unsigned char* lds, const Gemm g, const Sched& S, const Epi& E, const int tid) {
;     ...
;             PG8_LDA(At, 0, 1); PG8_STAGE(PG8_SB(0, 0), b2, voffB); PG8_STAGE(PG8_SB(0, 1), b2 + hstepB, voffB); PG8_STAGE(PG8_SA(0, 0), a2, voffA);
.Lbe4_0:
	s_add_i32 m0, s83, 0x2000
	s_add_u32 s84, s38, 0x10000
	v_lshl_add_u64 v[166:167], s[38:39], 0, v[140:141]
	s_addc_u32 s85, s39, 0
	s_add_i32 s83, s86, s55
	s_cmp_lg_u32 s32, 0
	s_cbranch_scc1 .Lbt4_1
	global_load_lds_dwordx4 v[166:167], off
	s_branch .Lbe4_1

; #define PG8_STAGE(bufoff, gbase, voff) do { _Pragma("unroll") for (int _i = 0; _i < 2; ++_i) \
;         __builtin_amdgcn_global_load_lds((const unsigned*)((const char*)(gbase) + (voff)[_i]), (PG8_LAS unsigned*)(lds + (bufoff) + ldsw + _i * 8192), 16, 0, 0); } while (0)
; #define PG8_LDA(dst, b, h) do { _Pragma("unroll") for (int m = 0; m < 4; ++m) _Pragma("unroll") for (int k = 0; k < 2; ++k) dst[m][k] = *(const PG8_LAS bf16x8*)(lds + PG8_SA(b, h) + aoff + m * 2048 + k * 1024); } while (0)
; template <class Epi, class Sched, bool ALIGN_EPI = false, bool SP2 = false>
; __device__ __forceinline__ void gemm_phase(PG8_LAS unsigned char* lds, const Gemm g, const Sched& S, const Epi& E, const int tid) {
;     ...
;             PG8_LDA(At, 0, 1); PG8_STAGE(PG8_SB(0, 0), b2, voffB); PG8_STAGE(PG8_SB(0, 1), b2 + hstepB, voffB); PG8_STAGE(PG8_SA(0, 0), a2, voffA);
.Lbe4_1:
	v_lshl_add_u64 v[236:237], s[84:85], 0, v[136:137]
	s_mov_b32 m0, s83
	v_lshl_add_u64 v[238:239], s[42:43], 0, v[138:139]
	s_cmp_lg_u32 s32, 0
	s_cbranch_scc1 .Lbt4_2
	global_load_lds_dwordx4 v[236:237], off
	s_branch .Lbe4_2

; #define PG8_STAGE(bufoff, gbase, voff) do { _Pragma("unroll") for (int _i = 0; _i < 2; ++_i) \
;         __builtin_amdgcn_global_load_lds((const unsigned*)((const char*)(gbase) + (voff)[_i]), (PG8_LAS unsigned*)(lds + (bufoff) + ldsw + _i * 8192), 16, 0, 0); } while (0)
; #define PG8_LDA(dst, b, h) do { _Pragma("unroll") for (int m = 0; m < 4; ++m) _Pragma("unroll") for (int k = 0; k < 2; ++k) dst[m][k] = *(const PG8_LAS bf16x8*)(lds + PG8_SA(b, h) + aoff + m * 2048 + k * 1024); } while (0)
; template <class Epi, class Sched, bool ALIGN_EPI = false, bool SP2 = false>
; __device__ __forceinline__ void gemm_phase(PG8_LAS unsigned char* lds, const Gemm g, const Sched& S, const Epi& E, const int tid) {
;     ...
;             PG8_LDA(At, 0, 1); PG8_STAGE(PG8_SB(0, 0), b2, voffB); PG8_STAGE(PG8_SB(0, 1), b2 + hstepB, voffB); PG8_STAGE(PG8_SA(0, 0), a2, voffA);
.Lbe4_2:
	v_lshl_add_u64 v[236:237], s[84:85], 0, v[140:141]
	s_add_i32 m0, s83, 0x2000
	s_nop 0
	s_cmp_lg_u32 s32, 0
	s_cbranch_scc1 .Lbt4_3
	global_load_lds_dwordx4 v[236:237], off
	s_branch .Lbe4_3

; #define PG8_STAGE(bufoff, gbase, voff) do { _Pragma("unroll") for (int _i = 0; _i < 2; ++_i) \
;         __builtin_amdgcn_global_load_lds((const unsigned*)((const char*)(gbase) + (voff)[_i]), (PG8_LAS unsigned*)(lds + (bufoff) + ldsw + _i * 8192), 16, 0, 0); } while (0)
; #define PG8_LDA(dst, b, h) do { _Pragma("unroll") for (int m = 0; m < 4; ++m) _Pragma("unroll") for (int k = 0; k < 2; ++k) dst[m][k] = *(const PG8_LAS bf16x8*)(lds + PG8_SA(b, h) + aoff + m * 2048 + k * 1024); } while (0)
; template <class Epi, class Sched, bool ALIGN_EPI = false, bool SP2 = false>
; __device__ __forceinline__ void gemm_phase(PG8_LAS unsigned char* lds, const Gemm g, const Sched& S, const Epi& E, const int tid) {
;     ...
;             PG8_LDA(At, 0, 1); PG8_STAGE(PG8_SB(0, 0), b2, voffB); PG8_STAGE(PG8_SB(0, 1), b2 + hstepB, voffB); PG8_STAGE(PG8_SA(0, 0), a2, voffA);
.Lbe4_3:
	v_lshl_add_u64 v[236:237], s[42:43], 0, v[134:135]
	s_mov_b32 m0, s31
	s_nop 0
	s_cmp_lg_u32 s32, 0
	s_cbranch_scc1 .Lbt4_4
	global_load_lds_dwordx4 v[236:237], off
	s_branch .Lbe4_4

; #define PG8_STAGE(bufoff, gbase, voff) do { _Pragma("unroll") for (int _i = 0; _i < 2; ++_i) \
;         __builtin_amdgcn_global_load_lds((const unsigned*)((const char*)(gbase) + (voff)[_i]), (PG8_LAS unsigned*)(lds + (bufoff) + ldsw + _i * 8192), 16, 0, 0); } while (0)
; #define PG8_LDA(dst, b, h) do { _Pragma("unroll") for (int m = 0; m < 4; ++m) _Pragma("unroll") for (int k = 0; k < 2; ++k) dst[m][k] = *(const PG8_LAS bf16x8*)(lds + PG8_SA(b, h) + aoff + m * 2048 + k * 1024); } while (0)
; template <class Epi, class Sched, bool ALIGN_EPI = false, bool SP2 = false>
; __device__ __forceinline__ void gemm_phase(PG8_LAS unsigned char* lds, const Gemm g, const Sched& S, const Epi& E, const int tid) {
;     ...
;             PG8_LDA(At, 0, 1); PG8_STAGE(PG8_SB(0, 0), b2, voffB); PG8_STAGE(PG8_SB(0, 1), b2 + hstepB, voffB); PG8_STAGE(PG8_SA(0, 0), a2, voffA);
.Lbe4_4:
	s_mov_b32 m0, s63
	s_nop 0
	s_cmp_lg_u32 s32, 0
	s_cbranch_scc1 .Lbt4_5
	global_load_lds_dwordx4 v[238:239], off
	s_branch .Lbe4_5

; #define PG8_STAGE(bufoff, gbase, voff) do { _Pragma("unroll") for (int _i = 0; _i < 2; ++_i) \
;         __builtin_amdgcn_global_load_lds((const unsigned*)((const char*)(gbase) + (voff)[_i]), (PG8_LAS unsigned*)(lds + (bufoff) + ldsw + _i * 8192), 16, 0, 0); } while (0)
; #define PG8_LDA(dst, b, h) do { _Pragma("unroll") for (int m = 0; m < 4; ++m) _Pragma("unroll") for (int k = 0; k < 2; ++k) dst[m][k] = *(const PG8_LAS bf16x8*)(lds + PG8_SA(b, h) + aoff + m * 2048 + k * 1024); } while (0)
; #define PG8_LDB(dst, b, h) do { _Pragma("unroll") for (int n = 0; n < 2; ++n) _Pragma("unroll") for (int k = 0; k < 2; ++k) dst[n][k] = *(const PG8_LAS bf16x8*)(lds + PG8_SB(b, h) + boff + n * 2048 + k * 1024); } while (0)
; #define PG8_MMA(ai, bj, At, Bt) do { __builtin_amdgcn_s_setprio(1); _Pragma("unroll") for (int m = 0; m < 4; ++m) _Pragma("unroll") for (int n = 0; n < 2; ++n) _Pragma("unroll") for (int k = 0; k < 2; ++k) \
;         acc[ai][bj][m][n] = __builtin_amdgcn_mfma_f32_16x16x32_bf16(Bt[n][k], At[m][k], acc[ai][bj][m][n], 0, 0, 0); __builtin_amdgcn_s_setprio(0); } while (0)
; #define PG8_WAIT_V(n) asm volatile("s_waitcnt vmcnt(" #n ")" ::: "memory")
; #define PG8_WAIT_L(n) asm volatile("s_waitcnt lgkmcnt(" #n ")" ::: "memory")
; #define PG8_BAR __builtin_amdgcn_s_barrier()
; #define PG8_SCHED __builtin_amdgcn_sched_barrier(0)
; template <class Epi, class Sched, bool ALIGN_EPI = false, bool SP2 = false>
; __device__ __forceinline__ void gemm_phase(PG8_LAS unsigned char* lds, const Gemm g, const Sched& S, const Epi& E, const int tid) {
;     ...
;             PG8_WAIT_V(8); PG8_WAIT_L(0); PG8_BAR; PG8_MMA(1, 0, At, B0); PG8_MMA(1, 1, At, B1); PG8_BAR; PG8_SCHED;
;             PG8_LDB(B0, 1, 0); PG8_LDB(B1, 1, 1); PG8_SCHED; PG8_LDA(At, 1, 0); PG8_STAGE(PG8_SA(0, 1), a2 + hstep, voffA);
.Lbe4_5:
	s_waitcnt vmcnt(8)
	s_waitcnt lgkmcnt(0)
	s_barrier
	s_setprio 1
	s_waitcnt lgkmcnt(0)
	v_mfma_f32_16x16x32_bf16 v[52:55], v[146:149], v[194:197], v[52:55]
	v_mfma_f32_16x16x32_bf16 v[60:63], v[170:173], v[194:197], v[60:63]
	v_mfma_f32_16x16x32_bf16 v[36:39], v[146:149], v[212:215], v[36:39]
	v_mfma_f32_16x16x32_bf16 v[44:47], v[170:173], v[212:215], v[44:47]
	v_mfma_f32_16x16x32_bf16 v[20:23], v[146:149], v[220:223], v[20:23]
	v_mfma_f32_16x16x32_bf16 v[28:31], v[170:173], v[220:223], v[28:31]
	v_mfma_f32_16x16x32_bf16 v[4:7], v[146:149], v[228:231], v[4:7]
	v_mfma_f32_16x16x32_bf16 v[12:15], v[170:173], v[228:231], v[12:15]
	v_mfma_f32_16x16x32_bf16 v[52:55], v[162:165], v[198:201], v[52:55]
	v_mfma_f32_16x16x32_bf16 v[60:63], v[174:177], v[198:201], v[60:63]
	v_mfma_f32_16x16x32_bf16 v[36:39], v[162:165], v[216:219], v[36:39]
	v_mfma_f32_16x16x32_bf16 v[44:47], v[174:177], v[216:219], v[44:47]
	v_mfma_f32_16x16x32_bf16 v[20:23], v[162:165], v[224:227], v[20:23]
	v_mfma_f32_16x16x32_bf16 v[28:31], v[174:177], v[224:227], v[28:31]
	v_mfma_f32_16x16x32_bf16 v[4:7], v[162:165], v[232:235], v[4:7]
	v_mfma_f32_16x16x32_bf16 v[12:15], v[174:177], v[232:235], v[12:15]
	s_setprio 0
	s_setprio 1
	v_mfma_f32_16x16x32_bf16 v[56:59], v[178:181], v[194:197], v[56:59]
	v_mfma_f32_16x16x32_bf16 v[64:67], v[186:189], v[194:197], v[64:67]
	v_mfma_f32_16x16x32_bf16 v[40:43], v[178:181], v[212:215], v[40:43]
	v_mfma_f32_16x16x32_bf16 v[48:51], v[186:189], v[212:215], v[48:51]
	v_mfma_f32_16x16x32_bf16 v[24:27], v[178:181], v[220:223], v[24:27]
	v_mfma_f32_16x16x32_bf16 v[32:35], v[186:189], v[220:223], v[32:35]
	v_mfma_f32_16x16x32_bf16 v[8:11], v[178:181], v[228:231], v[8:11]
	v_mfma_f32_16x16x32_bf16 v[16:19], v[186:189], v[228:231], v[16:19]
	v_mfma_f32_16x16x32_bf16 v[56:59], v[182:185], v[198:201], v[56:59]
	v_mfma_f32_16x16x32_bf16 v[64:67], v[190:193], v[198:201], v[64:67]
	v_mfma_f32_16x16x32_bf16 v[40:43], v[182:185], v[216:219], v[40:43]
	v_mfma_f32_16x16x32_bf16 v[48:51], v[190:193], v[216:219], v[48:51]
	v_mfma_f32_16x16x32_bf16 v[24:27], v[182:185], v[224:227], v[24:27]
	v_mfma_f32_16x16x32_bf16 v[32:35], v[190:193], v[224:227], v[32:35]
	v_mfma_f32_16x16x32_bf16 v[8:11], v[182:185], v[232:235], v[8:11]
	v_mfma_f32_16x16x32_bf16 v[16:19], v[190:193], v[232:235], v[16:19]
	s_setprio 0
	s_barrier
	s_add_i32 s83, 0, 0x18000
	v_add_u32_e32 v161, s83, v158
	s_add_i32 s84, 0, 0x1c000
	ds_read_b128 v[146:149], v161
	ds_read_b128 v[162:165], v161 offset:1024
	ds_read_b128 v[170:173], v161 offset:2048
	ds_read_b128 v[174:177], v161 offset:3072
	v_add_u32_e32 v161, s84, v158
	ds_read_b128 v[178:181], v161
	ds_read_b128 v[182:185], v161 offset:1024
	ds_read_b128 v[186:189], v161 offset:2048
	ds_read_b128 v[190:193], v161 offset:3072
	s_add_u32 s42, s42, 0x40000
	s_addc_u32 s43, s43, 0
	s_mov_b32 m0, s64
	v_lshl_add_u64 v[240:241], s[42:43], 0, v[134:135]
	ds_read_b128 v[194:197], v160 offset:32768
	ds_read_b128 v[198:201], v160 offset:33792
	ds_read_b128 v[212:215], v160 offset:34816
	ds_read_b128 v[216:219], v160 offset:35840
	ds_read_b128 v[220:223], v160 offset:36864
	ds_read_b128 v[224:227], v160 offset:37888
	ds_read_b128 v[228:231], v160 offset:38912
	ds_read_b128 v[232:235], v160 offset:39936
	s_cmp_lg_u32 s32, 0
	s_cbranch_scc1 .Lbt4_6
	global_load_lds_dwordx4 v[240:241], off
	s_branch .Lbe4_6

; #define PG8_STAGE(bufoff, gbase, voff) do { _Pragma("unroll") for (int _i = 0; _i < 2; ++_i) \
;         __builtin_amdgcn_global_load_lds((const unsigned*)((const char*)(gbase) + (voff)[_i]), (PG8_LAS unsigned*)(lds + (bufoff) + ldsw + _i * 8192), 16, 0, 0); } while (0)
; #define PG8_LDA(dst, b, h) do { _Pragma("unroll") for (int m = 0; m < 4; ++m) _Pragma("unroll") for (int k = 0; k < 2; ++k) dst[m][k] = *(const PG8_LAS bf16x8*)(lds + PG8_SA(b, h) + aoff + m * 2048 + k * 1024); } while (0)
; #define PG8_LDB(dst, b, h) do { _Pragma("unroll") for (int n = 0; n < 2; ++n) _Pragma("unroll") for (int k = 0; k < 2; ++k) dst[n][k] = *(const PG8_LAS bf16x8*)(lds + PG8_SB(b, h) + boff + n * 2048 + k * 1024); } while (0)
; #define PG8_SCHED __builtin_amdgcn_sched_barrier(0)
; template <class Epi, class Sched, bool ALIGN_EPI = false, bool SP2 = false>
; __device__ __forceinline__ void gemm_phase(PG8_LAS unsigned char* lds, const Gemm g, const Sched& S, const Epi& E, const int tid) {
;     ...
;             PG8_LDB(B0, 1, 0); PG8_LDB(B1, 1, 1); PG8_SCHED; PG8_LDA(At, 1, 0); PG8_STAGE(PG8_SA(0, 1), a2 + hstep, voffA);
.Lbe4_6:
	v_lshl_add_u64 v[240:241], s[42:43], 0, v[138:139]
	s_mov_b32 m0, s65
	s_nop 0
	s_cmp_lg_u32 s32, 0
	s_cbranch_scc1 .Lbt4_7
	global_load_lds_dwordx4 v[240:241], off
	s_branch .Lbe4_7

; #define PG8_STAGE(bufoff, gbase, voff) do { _Pragma("unroll") for (int _i = 0; _i < 2; ++_i) \
;         __builtin_amdgcn_global_load_lds((const unsigned*)((const char*)(gbase) + (voff)[_i]), (PG8_LAS unsigned*)(lds + (bufoff) + ldsw + _i * 8192), 16, 0, 0); } while (0)
; #define PG8_LDA(dst, b, h) do { _Pragma("unroll") for (int m = 0; m < 4; ++m) _Pragma("unroll") for (int k = 0; k < 2; ++k) dst[m][k] = *(const PG8_LAS bf16x8*)(lds + PG8_SA(b, h) + aoff + m * 2048 + k * 1024); } while (0)
; #define PG8_MMA(ai, bj, At, Bt) do { __builtin_amdgcn_s_setprio(1); _Pragma("unroll") for (int m = 0; m < 4; ++m) _Pragma("unroll") for (int n = 0; n < 2; ++n) _Pragma("unroll") for (int k = 0; k < 2; ++k) \
;         acc[ai][bj][m][n] = __builtin_amdgcn_mfma_f32_16x16x32_bf16(Bt[n][k], At[m][k], acc[ai][bj][m][n], 0, 0, 0); __builtin_amdgcn_s_setprio(0); } while (0)
; #define PG8_WAIT_V(n) asm volatile("s_waitcnt vmcnt(" #n ")" ::: "memory")
; #define PG8_WAIT_L(n) asm volatile("s_waitcnt lgkmcnt(" #n ")" ::: "memory")
; #define PG8_BAR __builtin_amdgcn_s_barrier()
; #define PG8_SCHED __builtin_amdgcn_sched_barrier(0)
; template <class Epi, class Sched, bool ALIGN_EPI = false, bool SP2 = false>
; __device__ __forceinline__ void gemm_phase(PG8_LAS unsigned char* lds, const Gemm g, const Sched& S, const Epi& E, const int tid) {
;     ...
;             PG8_WAIT_V(8); PG8_WAIT_L(0); PG8_BAR; PG8_MMA(0, 0, At, B0); PG8_MMA(0, 1, At, B1); PG8_BAR; PG8_SCHED;
;             PG8_LDA(At, 1, 1); PG8_STAGE(PG8_SB(1, 0), b3, voffB); PG8_STAGE(PG8_SB(1, 1), b3 + hstepB, voffB); PG8_STAGE(PG8_SA(1, 0), a3, voffA);
.Lbe4_7:
	s_waitcnt vmcnt(8)
	s_waitcnt lgkmcnt(0)
	s_barrier
	s_setprio 1
	s_waitcnt lgkmcnt(0)
	v_mfma_f32_16x16x32_bf16 v[120:123], v[146:149], v[194:197], v[120:123]
	v_mfma_f32_16x16x32_bf16 v[128:131], v[170:173], v[194:197], v[128:131]
	v_mfma_f32_16x16x32_bf16 v[100:103], v[146:149], v[212:215], v[100:103]
	v_mfma_f32_16x16x32_bf16 v[108:111], v[170:173], v[212:215], v[108:111]
	v_mfma_f32_16x16x32_bf16 v[84:87], v[146:149], v[220:223], v[84:87]
	v_mfma_f32_16x16x32_bf16 v[92:95], v[170:173], v[220:223], v[92:95]
	v_mfma_f32_16x16x32_bf16 v[68:71], v[146:149], v[228:231], v[68:71]
	v_mfma_f32_16x16x32_bf16 v[76:79], v[170:173], v[228:231], v[76:79]
	v_mfma_f32_16x16x32_bf16 v[120:123], v[162:165], v[198:201], v[120:123]
	v_mfma_f32_16x16x32_bf16 v[128:131], v[174:177], v[198:201], v[128:131]
	v_mfma_f32_16x16x32_bf16 v[100:103], v[162:165], v[216:219], v[100:103]
	v_mfma_f32_16x16x32_bf16 v[108:111], v[174:177], v[216:219], v[108:111]
	v_mfma_f32_16x16x32_bf16 v[84:87], v[162:165], v[224:227], v[84:87]
	v_mfma_f32_16x16x32_bf16 v[92:95], v[174:177], v[224:227], v[92:95]
	v_mfma_f32_16x16x32_bf16 v[68:71], v[162:165], v[232:235], v[68:71]
	v_mfma_f32_16x16x32_bf16 v[76:79], v[174:177], v[232:235], v[76:79]
	s_setprio 0
	s_setprio 1
	v_mfma_f32_16x16x32_bf16 v[116:119], v[178:181], v[194:197], v[116:119]
	v_mfma_f32_16x16x32_bf16 v[124:127], v[186:189], v[194:197], v[124:127]
	v_mfma_f32_16x16x32_bf16 v[104:107], v[178:181], v[212:215], v[104:107]
	v_mfma_f32_16x16x32_bf16 v[112:115], v[186:189], v[212:215], v[112:115]
	v_mfma_f32_16x16x32_bf16 v[88:91], v[178:181], v[220:223], v[88:91]
	v_mfma_f32_16x16x32_bf16 v[96:99], v[186:189], v[220:223], v[96:99]
	v_mfma_f32_16x16x32_bf16 v[72:75], v[178:181], v[228:231], v[72:75]
	v_mfma_f32_16x16x32_bf16 v[80:83], v[186:189], v[228:231], v[80:83]
	v_mfma_f32_16x16x32_bf16 v[116:119], v[182:185], v[198:201], v[116:119]
	v_mfma_f32_16x16x32_bf16 v[124:127], v[190:193], v[198:201], v[124:127]
	v_mfma_f32_16x16x32_bf16 v[104:107], v[182:185], v[216:219], v[104:107]
	v_mfma_f32_16x16x32_bf16 v[112:115], v[190:193], v[216:219], v[112:115]
	v_mfma_f32_16x16x32_bf16 v[88:91], v[182:185], v[224:227], v[88:91]
	v_mfma_f32_16x16x32_bf16 v[96:99], v[190:193], v[224:227], v[96:99]
	v_mfma_f32_16x16x32_bf16 v[72:75], v[182:185], v[232:235], v[72:75]
	v_mfma_f32_16x16x32_bf16 v[80:83], v[190:193], v[232:235], v[80:83]
	s_setprio 0
	s_barrier
	s_add_i32 s42, s83, s55
	v_lshl_add_u64 v[150:151], v[150:151], 0, s[52:53]
	s_mov_b32 m0, s42
	ds_read_b128 v[194:197], v160 offset:49152
	ds_read_b128 v[198:201], v160 offset:50176
	ds_read_b128 v[212:215], v160 offset:51200
	ds_read_b128 v[216:219], v160 offset:52224
	ds_read_b128 v[220:223], v160 offset:53248
	ds_read_b128 v[224:227], v160 offset:54272
	ds_read_b128 v[228:231], v160 offset:55296
	ds_read_b128 v[232:235], v160 offset:56320
	s_cmp_lg_u32 s32, 0
	s_cbranch_scc1 .Lbt4_8
	global_load_lds_dwordx4 v[150:151], off

; #define PG8_STAGE(bufoff, gbase, voff) do { _Pragma("unroll") for (int _i = 0; _i < 2; ++_i) \
;         __builtin_amdgcn_global_load_lds((const unsigned*)((const char*)(gbase) + (voff)[_i]), (PG8_LAS unsigned*)(lds + (bufoff) + ldsw + _i * 8192), 16, 0, 0); } while (0)
; #define PG8_LDA(dst, b, h) do { _Pragma("unroll") for (int m = 0; m < 4; ++m) _Pragma("unroll") for (int k = 0; k < 2; ++k) dst[m][k] = *(const PG8_LAS bf16x8*)(lds + PG8_SA(b, h) + aoff + m * 2048 + k * 1024); } while (0)
; template <class Epi, class Sched, bool ALIGN_EPI = false, bool SP2 = false>
; __device__ __forceinline__ void gemm_phase(PG8_LAS unsigned char* lds, const Gemm g, const Sched& S, const Epi& E, const int tid) {
;     ...
;             PG8_LDA(At, 1, 1); PG8_STAGE(PG8_SB(1, 0), b3, voffB); PG8_STAGE(PG8_SB(1, 1), b3 + hstepB, voffB); PG8_STAGE(PG8_SA(1, 0), a3, voffA);
.Lbt4_11:
	v_lshl_add_u64 v[150:151], v[236:237], 0, s[52:53]
	s_mov_b32 m0, s66
	s_nop 0
	s_cmp_lg_u32 s32, 0
	s_cbranch_scc1 .Lbt4_12
	global_load_lds_dwordx4 v[150:151], off
	s_branch .Lbe4_12

; #define PG8_STAGE(bufoff, gbase, voff) do { _Pragma("unroll") for (int _i = 0; _i < 2; ++_i) \
;         __builtin_amdgcn_global_load_lds((const unsigned*)((const char*)(gbase) + (voff)[_i]), (PG8_LAS unsigned*)(lds + (bufoff) + ldsw + _i * 8192), 16, 0, 0); } while (0)
; #define PG8_LDA(dst, b, h) do { _Pragma("unroll") for (int m = 0; m < 4; ++m) _Pragma("unroll") for (int k = 0; k < 2; ++k) dst[m][k] = *(const PG8_LAS bf16x8*)(lds + PG8_SA(b, h) + aoff + m * 2048 + k * 1024); } while (0)
; template <class Epi, class Sched, bool ALIGN_EPI = false, bool SP2 = false>
; __device__ __forceinline__ void gemm_phase(PG8_LAS unsigned char* lds, const Gemm g, const Sched& S, const Epi& E, const int tid) {
;     ...
;             PG8_LDA(At, 1, 1); PG8_STAGE(PG8_SB(1, 0), b3, voffB); PG8_STAGE(PG8_SB(1, 1), b3 + hstepB, voffB); PG8_STAGE(PG8_SA(1, 0), a3, voffA);
.Lbe4_12:
	v_lshl_add_u64 v[150:151], v[238:239], 0, s[52:53]
	s_mov_b32 m0, s67
	s_nop 0
	s_cmp_lg_u32 s32, 0
	s_cbranch_scc1 .Lbt4_13
	global_load_lds_dwordx4 v[150:151], off
	s_branch .Lbe4_13

; template <int RA, int NP, int NS, int KT, class R8>
; DI void small_gemm(LAS unsigned char* lds, const bf16* __restrict__ A, const bf16* __restrict__ Bt, int K, int row_base, int col_base, const R8& e, int tid, int wave, int lane) {
;     ...
;     for (int s = 0; s < NS - 1; ++s) SG_STAGE(s, s);
.LBB0_1269:
	s_cmp_lg_u32 s32, 0
	s_cbranch_scc0 .Leh4_e
	v_lshl_add_u64 v[252:253], v[252:253], 0, s[52:53]
	v_lshl_add_u64 v[254:255], v[254:255], 0, s[52:53]
	s_add_i32 m0, s31, 0xc000
	s_nop 0
	global_load_lds_dwordx4 v[252:253], off
	s_add_i32 m0, s31, 0xe000
	s_nop 0
	global_load_lds_dwordx4 v[254:255], off

;     DI bool next(int i, Unit& u) const { const int L = i * 32 + rank; if (L >= ppg * nN) return false; u.pm = ppg * grp + (L % ppg); const int p0 = L / ppg, p1 = p0 + rot; u.pn = rev ? nN - 1 - p0 : (p1 >= nN ? p1 - nN : p1); return true; }
; template <class Epi, class Sched, bool ALIGN_EPI = false, bool SP2 = false>
; __device__ __forceinline__ void gemm_phase(PG8_LAS unsigned char* lds, const Gemm g, const Sched& S, const Epi& E, const int tid) {
;     ...
;         const bool has_next = S.next(ui + 1, nxt);
;         const char* nA = has_next ? (const char*)g.A + (size_t)nxt.pm * tstep : cA; const char* nB = has_next ? (const char*)g.Bt + (size_t)nxt.pn * tstep : cB;
;         for (int t = 0; t < nt; t += 2) {
;             const bool last = (t == nt - 2);
;             const char* a1 = cA + (size_t)(t + 1) * kstep;
;             const char* a2 = last ? nA : cA + (size_t)(t + 2) * kstep; const char* b2 = last ? nB : cB + (size_t)(t + 2) * kstep;
;             const char* a3 = a2 + kstep; const char* b3 = b2 + kstep;
; template <int RA, int NP, int NS, int KT, class R8>
; DI void small_gemm(LAS unsigned char* lds, const bf16* __restrict__ A, const bf16* __restrict__ Bt, int K, int row_base, int col_base, const R8& e, int tid, int wave, int lane) {
;     ...
;     int R, Cc; pg8::stage_rc(tid * 16, R, Cc);
;     const int Rb = (R & ~31) + pg8::perm32(R & 31);
;     const bf16* asrc = A + (size_t)(row_base + R) * K + Cc;
;     const bf16* bsrc = Bt + (size_t)(col_base + Rb) * K + Cc;
;     const size_t bgrp = (size_t)64 * K;
;     const int NT = K / (64 * KT);
.LBB0_1460:
	s_add_u32 s36, s38, 0xfff00080
	s_addc_u32 s37, s39, -1
	s_add_i32 s81, 0, 0x10000
	s_cmp_eq_u32 s80, 60
	s_cselect_b32 s41, s19, s37
	s_cselect_b32 s40, s25, s36
	v_add_u32_e32 v150, s81, v158
	s_cselect_b32 s37, s17, s79
	s_cselect_b32 s36, s76, s78
	s_cmp_eq_u32 s80, 60
	s_cselect_b32 s32, 1, 0
	s_andn2_b32 s32, s32, s30
	s_cmp_lg_u32 s32, 0
	s_cbranch_scc0 .Leh1460_t
	s_lshl_b32 s92, s3, 2
	s_andn2_b32 s92, s92, 63
	s_lshl_b32 s93, s34, 6
	v_and_b32_e32 v212, 0xffffffe0, v133
	v_or_b32_e32 v214, s92, v154
	s_lshl_b32 s98, s27, 7
	s_and_b32 s93, s93, 64
	v_and_b32_e32 v213, 24, v155
	v_add_u32_e32 v212, v214, v212
	s_or_b32 s98, s93, s98
	s_lshr_b32 s93, s42, 31
	v_or3_b32 v212, v212, v213, v153
	s_bitset1_b32 s98, 14
	s_add_i32 s93, s42, s93
	v_ashrrev_i32_e32 v213, 31, v212
	s_ashr_i32 s99, s93, 1
	v_add_u32_e32 v216, s98, v133
	v_lshlrev_b64 v[212:213], 13, v[212:213]
	v_ashrrev_i32_e32 v217, 31, v216
	v_lshl_add_u64 v[212:213], s[10:11], 0, v[212:213]
	s_lshl_b32 s41, s99, 4
	v_mov_b32_e32 v234, v132
	v_ashrrev_i32_e32 v235, 31, v132
	s_add_i32 s98, s98, s41
	v_lshlrev_b64 v[216:217], 13, v[216:217]
	v_lshlrev_b64 v[218:219], 1, v[234:235]
	v_or_b32_e32 v224, s98, v152
	v_lshl_add_u64 v[216:217], s[6:7], 0, v[216:217]
	s_add_i32 s98, s43, 0
	v_lshl_add_u64 v[230:231], v[216:217], 0, v[218:219]
	v_lshl_add_u64 v[228:229], v[212:213], 0, v[218:219]
	s_mov_b32 s100, 0x200
	s_mov_b32 s101, 0
	v_lshl_add_u64 v[252:253], v[230:231], 0, s[100:101]
	v_lshl_add_u64 v[254:255], v[228:229], 0, s[100:101]
	s_mov_b32 s100, 0xfffffd80
	s_mov_b32 s101, -1

; #define PG8_STAGE(bufoff, gbase, voff) do { _Pragma("unroll") for (int _i = 0; _i < 2; ++_i) \
;         __builtin_amdgcn_global_load_lds((const unsigned*)((const char*)(gbase) + (voff)[_i]), (PG8_LAS unsigned*)(lds + (bufoff) + ldsw + _i * 8192), 16, 0, 0); } while (0)
; #define PG8_LDA(dst, b, h) do { _Pragma("unroll") for (int m = 0; m < 4; ++m) _Pragma("unroll") for (int k = 0; k < 2; ++k) dst[m][k] = *(const PG8_LAS bf16x8*)(lds + PG8_SA(b, h) + aoff + m * 2048 + k * 1024); } while (0)
; template <class Epi, class Sched, bool ALIGN_EPI = false, bool SP2 = false>
; __device__ __forceinline__ void gemm_phase(PG8_LAS unsigned char* lds, const Gemm g, const Sched& S, const Epi& E, const int tid) {
;     ...
;             PG8_LDA(At, 0, 1); PG8_STAGE(PG8_SB(0, 0), b2, voffB); PG8_STAGE(PG8_SB(0, 1), b2 + hstepB, voffB); PG8_STAGE(PG8_SA(0, 0), a2, voffA);
.Lbe1460_0:
	s_add_i32 m0, s81, 0x2000
	s_add_u32 s82, s36, 0x40000
	v_lshl_add_u64 v[166:167], s[36:37], 0, v[140:141]
	s_addc_u32 s83, s37, 0
	s_add_i32 s81, s84, s43
	s_cmp_lg_u32 s32, 0
	s_cbranch_scc1 .Lbt1460_1
	global_load_lds_dwordx4 v[166:167], off
	s_branch .Lbe1460_1

; #define PG8_STAGE(bufoff, gbase, voff) do { _Pragma("unroll") for (int _i = 0; _i < 2; ++_i) \
;         __builtin_amdgcn_global_load_lds((const unsigned*)((const char*)(gbase) + (voff)[_i]), (PG8_LAS unsigned*)(lds + (bufoff) + ldsw + _i * 8192), 16, 0, 0); } while (0)
; #define PG8_LDA(dst, b, h) do { _Pragma("unroll") for (int m = 0; m < 4; ++m) _Pragma("unroll") for (int k = 0; k < 2; ++k) dst[m][k] = *(const PG8_LAS bf16x8*)(lds + PG8_SA(b, h) + aoff + m * 2048 + k * 1024); } while (0)
; #define PG8_LDB(dst, b, h) do { _Pragma("unroll") for (int n = 0; n < 2; ++n) _Pragma("unroll") for (int k = 0; k < 2; ++k) dst[n][k] = *(const PG8_LAS bf16x8*)(lds + PG8_SB(b, h) + boff + n * 2048 + k * 1024); } while (0)
; #define PG8_MMA(ai, bj, At, Bt) do { __builtin_amdgcn_s_setprio(1); _Pragma("unroll") for (int m = 0; m < 4; ++m) _Pragma("unroll") for (int n = 0; n < 2; ++n) _Pragma("unroll") for (int k = 0; k < 2; ++k) \
;         acc[ai][bj][m][n] = __builtin_amdgcn_mfma_f32_16x16x32_bf16(Bt[n][k], At[m][k], acc[ai][bj][m][n], 0, 0, 0); __builtin_amdgcn_s_setprio(0); } while (0)
; #define PG8_WAIT_V(n) asm volatile("s_waitcnt vmcnt(" #n ")" ::: "memory")
; #define PG8_WAIT_L(n) asm volatile("s_waitcnt lgkmcnt(" #n ")" ::: "memory")
; #define PG8_BAR __builtin_amdgcn_s_barrier()
; #define PG8_SCHED __builtin_amdgcn_sched_barrier(0)
; template <class Epi, class Sched, bool ALIGN_EPI = false, bool SP2 = false>
; __device__ __forceinline__ void gemm_phase(PG8_LAS unsigned char* lds, const Gemm g, const Sched& S, const Epi& E, const int tid) {
;     ...
;             PG8_WAIT_V(8); PG8_WAIT_L(0); PG8_BAR; PG8_MMA(1, 0, At, B0); PG8_MMA(1, 1, At, B1); PG8_BAR; PG8_SCHED;
;             PG8_LDB(B0, 1, 0); PG8_LDB(B1, 1, 1); PG8_SCHED; PG8_LDA(At, 1, 0); PG8_STAGE(PG8_SA(0, 1), a2 + hstep, voffA);
.Lbe1460_5:
	s_waitcnt vmcnt(8)
	s_waitcnt lgkmcnt(0)
	s_barrier
	s_setprio 1
	s_waitcnt lgkmcnt(0)
	v_mfma_f32_16x16x32_bf16 v[52:55], v[146:149], v[194:197], v[52:55]
	v_mfma_f32_16x16x32_bf16 v[60:63], v[170:173], v[194:197], v[60:63]
	v_mfma_f32_16x16x32_bf16 v[36:39], v[146:149], v[212:215], v[36:39]
	v_mfma_f32_16x16x32_bf16 v[44:47], v[170:173], v[212:215], v[44:47]
	v_mfma_f32_16x16x32_bf16 v[20:23], v[146:149], v[220:223], v[20:23]
	v_mfma_f32_16x16x32_bf16 v[28:31], v[170:173], v[220:223], v[28:31]
	v_mfma_f32_16x16x32_bf16 v[4:7], v[146:149], v[228:231], v[4:7]
	v_mfma_f32_16x16x32_bf16 v[12:15], v[170:173], v[228:231], v[12:15]
	v_mfma_f32_16x16x32_bf16 v[52:55], v[162:165], v[198:201], v[52:55]
	v_mfma_f32_16x16x32_bf16 v[60:63], v[174:177], v[198:201], v[60:63]
	v_mfma_f32_16x16x32_bf16 v[36:39], v[162:165], v[216:219], v[36:39]
	v_mfma_f32_16x16x32_bf16 v[44:47], v[174:177], v[216:219], v[44:47]
	v_mfma_f32_16x16x32_bf16 v[20:23], v[162:165], v[224:227], v[20:23]
	v_mfma_f32_16x16x32_bf16 v[28:31], v[174:177], v[224:227], v[28:31]
	v_mfma_f32_16x16x32_bf16 v[4:7], v[162:165], v[232:235], v[4:7]
	v_mfma_f32_16x16x32_bf16 v[12:15], v[174:177], v[232:235], v[12:15]
	s_setprio 0
	s_setprio 1
	v_mfma_f32_16x16x32_bf16 v[56:59], v[178:181], v[194:197], v[56:59]
	v_mfma_f32_16x16x32_bf16 v[64:67], v[186:189], v[194:197], v[64:67]
	v_mfma_f32_16x16x32_bf16 v[40:43], v[178:181], v[212:215], v[40:43]
	v_mfma_f32_16x16x32_bf16 v[48:51], v[186:189], v[212:215], v[48:51]
	v_mfma_f32_16x16x32_bf16 v[24:27], v[178:181], v[220:223], v[24:27]
	v_mfma_f32_16x16x32_bf16 v[32:35], v[186:189], v[220:223], v[32:35]
	v_mfma_f32_16x16x32_bf16 v[8:11], v[178:181], v[228:231], v[8:11]
	v_mfma_f32_16x16x32_bf16 v[16:19], v[186:189], v[228:231], v[16:19]
	v_mfma_f32_16x16x32_bf16 v[56:59], v[182:185], v[198:201], v[56:59]
	v_mfma_f32_16x16x32_bf16 v[64:67], v[190:193], v[198:201], v[64:67]
	v_mfma_f32_16x16x32_bf16 v[40:43], v[182:185], v[216:219], v[40:43]
	v_mfma_f32_16x16x32_bf16 v[48:51], v[190:193], v[216:219], v[48:51]
	v_mfma_f32_16x16x32_bf16 v[24:27], v[182:185], v[224:227], v[24:27]
	v_mfma_f32_16x16x32_bf16 v[32:35], v[190:193], v[224:227], v[32:35]
	v_mfma_f32_16x16x32_bf16 v[8:11], v[182:185], v[232:235], v[8:11]
	v_mfma_f32_16x16x32_bf16 v[16:19], v[190:193], v[232:235], v[16:19]
	s_setprio 0
	s_barrier
	s_add_i32 s81, 0, 0x18000
	v_add_u32_e32 v161, s81, v158
	s_add_i32 s82, 0, 0x1c000
	ds_read_b128 v[146:149], v161
	ds_read_b128 v[162:165], v161 offset:1024
	ds_read_b128 v[170:173], v161 offset:2048
	ds_read_b128 v[174:177], v161 offset:3072
	v_add_u32_e32 v161, s82, v158
	ds_read_b128 v[178:181], v161
	ds_read_b128 v[182:185], v161 offset:1024
	ds_read_b128 v[186:189], v161 offset:2048
	ds_read_b128 v[190:193], v161 offset:3072
	s_add_u32 s40, s40, 0x100000
	s_addc_u32 s41, s41, 0
	s_mov_b32 m0, s62
	v_lshl_add_u64 v[240:241], s[40:41], 0, v[134:135]
	ds_read_b128 v[194:197], v160 offset:32768
	ds_read_b128 v[198:201], v160 offset:33792
	ds_read_b128 v[212:215], v160 offset:34816
	ds_read_b128 v[216:219], v160 offset:35840
	ds_read_b128 v[220:223], v160 offset:36864
	ds_read_b128 v[224:227], v160 offset:37888
	ds_read_b128 v[228:231], v160 offset:38912
	ds_read_b128 v[232:235], v160 offset:39936
	s_cmp_lg_u32 s32, 0
	s_cbranch_scc1 .Lbt1460_6
	global_load_lds_dwordx4 v[240:241], off
	s_branch .Lbe1460_6

; __global__ void __launch_bounds__(NTHREADS, 2) hybrid_fwd(Args Aval) {
	.amdhsa_kernel _Z10hybrid_fwd4Args
		.amdhsa_group_segment_fixed_size 0
		.amdhsa_private_segment_fixed_size 0
		.amdhsa_kernarg_size 536
		.amdhsa_user_sgpr_count 2
		.amdhsa_user_sgpr_dispatch_ptr 0
		.amdhsa_user_sgpr_queue_ptr 0
		.amdhsa_user_sgpr_kernarg_segment_ptr 1
		.amdhsa_user_sgpr_dispatch_id 0
		.amdhsa_user_sgpr_kernarg_preload_length 0
		.amdhsa_user_sgpr_kernarg_preload_offset 0
		.amdhsa_user_sgpr_private_segment_size 0
		.amdhsa_uses_dynamic_stack 0
		.amdhsa_enable_private_segment 0
		.amdhsa_system_sgpr_workgroup_id_x 1
		.amdhsa_system_sgpr_workgroup_id_y 0
		.amdhsa_system_sgpr_workgroup_id_z 0
		.amdhsa_system_sgpr_workgroup_info 0
		.amdhsa_system_vgpr_workitem_id 0
		.amdhsa_next_free_vgpr 256
		.amdhsa_next_free_sgpr 102
		.amdhsa_accum_offset 256
		.amdhsa_reserve_vcc 1
		.amdhsa_float_round_mode_32 0
		.amdhsa_float_round_mode_16_64 0
		.amdhsa_float_denorm_mode_32 3
		.amdhsa_float_denorm_mode_16_64 3
		.amdhsa_dx10_clamp 1
		.amdhsa_ieee_mode 1
		.amdhsa_fp16_overflow 0
		.amdhsa_tg_split 0
		.amdhsa_exception_fp_ieee_invalid_op 0
		.amdhsa_exception_fp_denorm_src 0
		.amdhsa_exception_fp_ieee_div_zero 0
		.amdhsa_exception_fp_ieee_overflow 0
		.amdhsa_exception_fp_ieee_underflow 0
		.amdhsa_exception_fp_ieee_inexact 0
		.amdhsa_exception_int_div_zero 0
	.end_amdhsa_kernel

; __global__ void __launch_bounds__(NTHREADS, 2) hybrid_fwd(Args Aval) {
amdhsa.kernels:
  - .agpr_count:     0
    .args:
      - .offset:         0
        .size:           280
        .value_kind:     by_value
      - .offset:         280
        .size:           4
        .value_kind:     hidden_block_count_x
      - .offset:         284
        .size:           4
        .value_kind:     hidden_block_count_y
      - .offset:         288
        .size:           4
        .value_kind:     hidden_block_count_z
      - .offset:         292
        .size:           2
        .value_kind:     hidden_group_size_x
      - .offset:         294
        .size:           2
        .value_kind:     hidden_group_size_y
      - .offset:         296
        .size:           2
        .value_kind:     hidden_group_size_z
      - .offset:         298
        .size:           2
        .value_kind:     hidden_remainder_x
      - .offset:         300
        .size:           2
        .value_kind:     hidden_remainder_y
      - .offset:         302
        .size:           2
        .value_kind:     hidden_remainder_z
      - .offset:         320
        .size:           8
        .value_kind:     hidden_global_offset_x
      - .offset:         328
        .size:           8
        .value_kind:     hidden_global_offset_y
      - .offset:         336
        .size:           8
        .value_kind:     hidden_global_offset_z
      - .offset:         344
        .size:           2
        .value_kind:     hidden_grid_dims
      - .offset:         400
        .size:           4
        .value_kind:     hidden_dynamic_lds_size
    .group_segment_fixed_size: 0
    .kernarg_segment_align: 8
    .kernarg_segment_size: 536
    .language:       OpenCL C
    .language_version:
      - 2
      - 0
    .max_flat_workgroup_size: 512
    .name:           _Z10hybrid_fwd4Args
    .private_segment_fixed_size: 0
    .sgpr_count:     108
    .sgpr_spill_count: 12
    .symbol:         _Z10hybrid_fwd4Args.kd
    .uniform_work_group_size: 1
    .uses_dynamic_stack: false
    .vgpr_count:     256
    .vgpr_spill_count: 0
    .wavefront_size: 64
